# conv: sliding-window register reuse (46 LDS reads instead of 496); RG-LRU gate matmul: plain FMAs with prefetched LDS operands; rnn2 carry fold loads batched
# speedup vs baseline: 1.1044x; 1.0161x over previous
; __device__ void rnn2_item(const Params& p, int item, char* smem) {
;     ...
;         const int w = tid >> 6, c = tid & 63, j0 = (j * w) >> 2, j1 = (j * (w + 1)) >> 2;
;         float a = 1.f, bb = 0.f;
;         const f32x2* ab = (const f32x2*)p.AB + ((size_t)b * 128) * 256 + hb * 64 + c;
; #pragma unroll 16
;         for (int jp = j0; jp < j1; ++jp) { const f32x2 v = ab[(size_t)jp * 256]; bb = v.x * bb + v.y; a *= v.x; }
;         sSeg[(w * 2 + 0) * 64 + c] = a; sSeg[(w * 2 + 1) * 64 + c] = bb;
;     }
.LBB0_143:
	v_mov_b32_e32 v36, v126
	s_bfe_u32 s12, s10, 0x70002
	s_ashr_i32 s0, s10, 9
	v_ashrrev_i32_e32 v37, 6, v36
	v_mul_lo_u32 v0, v37, s12
	v_ashrrev_i32_e32 v2, 2, v0
	v_add_u32_e32 v0, s12, v0
	v_ashrrev_i32_e32 v39, 2, v0
	v_and_b32_e32 v38, 63, v36
	s_ashr_i32 s1, s0, 31
	v_cmp_lt_i32_e32 vcc, v2, v39
	v_mov_b32_e32 v35, 0
	v_mov_b32_e32 v40, 1.0
	s_and_saveexec_b64 s[22:23], vcc
	s_cbranch_execz .LBB0_153
	v_readfirstlane_b32 s14, v2
	v_readfirstlane_b32 s15, v39
	s_lshl_b32 s13, s11, 3
	s_and_b32 s13, s13, 0x600
	s_lshl_b64 s[36:37], s[0:1], 18
	v_readlane_b32 s40, v165, 26
	v_readlane_b32 s41, v165, 27
	v_readlane_b32 s42, v165, 28
	v_readlane_b32 s43, v165, 29
	v_readlane_b32 s44, v165, 30
	v_readlane_b32 s45, v165, 31
	v_readlane_b32 s46, v165, 32
	v_readlane_b32 s47, v165, 33
	v_readlane_b32 s48, v165, 34
	v_readlane_b32 s49, v165, 35
	v_readlane_b32 s50, v165, 36
	v_readlane_b32 s51, v165, 37
	v_readlane_b32 s52, v165, 38
	v_readlane_b32 s53, v165, 39
	v_readlane_b32 s54, v165, 40
	v_readlane_b32 s55, v165, 41
	s_add_u32 s34, s42, s13
	s_addc_u32 s35, s43, 0
	s_add_u32 s34, s34, s36
	s_addc_u32 s35, s35, s37
	v_lshlrev_b32_e32 v112, 3, v38
	v_mov_b32_e32 v35, 0
	v_mov_b32_e32 v40, 1.0
	s_add_i32 s38, s15, -1
.Lfold_chunk:
	s_add_i32 s39, s14, 0
	s_min_i32 s39, s39, s38
	s_lshl_b32 s39, s39, 11
	v_add_u32_e32 v0, s39, v112
	global_load_dwordx2 v[4:5], v0, s[34:35]
	s_add_i32 s39, s14, 1
	s_min_i32 s39, s39, s38
	s_lshl_b32 s39, s39, 11
	v_add_u32_e32 v0, s39, v112
	global_load_dwordx2 v[6:7], v0, s[34:35]
	s_add_i32 s39, s14, 2
	s_min_i32 s39, s39, s38
	s_lshl_b32 s39, s39, 11
	v_add_u32_e32 v0, s39, v112
	global_load_dwordx2 v[8:9], v0, s[34:35]
	s_add_i32 s39, s14, 3
	s_min_i32 s39, s39, s38
	s_lshl_b32 s39, s39, 11
	v_add_u32_e32 v0, s39, v112
	global_load_dwordx2 v[10:11], v0, s[34:35]
	s_add_i32 s39, s14, 4
	s_min_i32 s39, s39, s38
	s_lshl_b32 s39, s39, 11
	v_add_u32_e32 v0, s39, v112
	global_load_dwordx2 v[12:13], v0, s[34:35]
	s_add_i32 s39, s14, 5
	s_min_i32 s39, s39, s38
	s_lshl_b32 s39, s39, 11
	v_add_u32_e32 v0, s39, v112
	global_load_dwordx2 v[14:15], v0, s[34:35]
	s_add_i32 s39, s14, 6
	s_min_i32 s39, s39, s38
	s_lshl_b32 s39, s39, 11
	v_add_u32_e32 v0, s39, v112
	global_load_dwordx2 v[16:17], v0, s[34:35]
	s_add_i32 s39, s14, 7
	s_min_i32 s39, s39, s38
	s_lshl_b32 s39, s39, 11
	v_add_u32_e32 v0, s39, v112
	global_load_dwordx2 v[18:19], v0, s[34:35]
	s_add_i32 s39, s14, 0
	s_cmp_ge_i32 s39, s15
	s_cbranch_scc1 .Lfold_done
	s_waitcnt vmcnt(7)
	v_fma_f32 v35, v4, v35, v5
	v_mul_f32_e32 v40, v40, v4
	s_add_i32 s39, s14, 1
	s_cmp_ge_i32 s39, s15
	s_cbranch_scc1 .Lfold_done
	s_waitcnt vmcnt(6)
	v_fma_f32 v35, v6, v35, v7
	v_mul_f32_e32 v40, v40, v6
	s_add_i32 s39, s14, 2
	s_cmp_ge_i32 s39, s15
	s_cbranch_scc1 .Lfold_done
	s_waitcnt vmcnt(5)
	v_fma_f32 v35, v8, v35, v9
	v_mul_f32_e32 v40, v40, v8
	s_add_i32 s39, s14, 3
	s_cmp_ge_i32 s39, s15
	s_cbranch_scc1 .Lfold_done
	s_waitcnt vmcnt(4)
	v_fma_f32 v35, v10, v35, v11
	v_mul_f32_e32 v40, v40, v10
	s_add_i32 s39, s14, 4
	s_cmp_ge_i32 s39, s15
	s_cbranch_scc1 .Lfold_done
	s_waitcnt vmcnt(3)
	v_fma_f32 v35, v12, v35, v13
	v_mul_f32_e32 v40, v40, v12
	s_add_i32 s39, s14, 5
	s_cmp_ge_i32 s39, s15
	s_cbranch_scc1 .Lfold_done
	s_waitcnt vmcnt(2)
	v_fma_f32 v35, v14, v35, v15
	v_mul_f32_e32 v40, v40, v14
	s_add_i32 s39, s14, 6
	s_cmp_ge_i32 s39, s15
	s_cbranch_scc1 .Lfold_done
	s_waitcnt vmcnt(1)
	v_fma_f32 v35, v16, v35, v17
	v_mul_f32_e32 v40, v40, v16
	s_add_i32 s39, s14, 7
	s_cmp_ge_i32 s39, s15
	s_cbranch_scc1 .Lfold_done
	s_waitcnt vmcnt(0)
	v_fma_f32 v35, v18, v35, v19
	v_mul_f32_e32 v40, v40, v18
	s_add_i32 s14, s14, 8
	s_cmp_lt_i32 s14, s15
	s_cbranch_scc1 .Lfold_chunk
.Lfold_done:
	s_waitcnt vmcnt(0)
	s_mov_b64 s[36:37], 0

; __device__ __forceinline__ float bf2f(bf16_t b) { return __uint_as_float(((unsigned)b) << 16); }
; __device__ void conv_item(const Params& p, int l, int item, char* smem) {
;     ...
;     __syncthreads();
; #pragma unroll 1
;     for (int tl = 0; tl < 16; ++tl) {
;         float y = bias;
; #pragma unroll
;         for (int k = 0; k < 31; ++k) y += wk[k] * bf2f(sG[(tl + k) * 256 + tid]);
;         sY[tl * 256 + tid] = y;
;     }
.LBB0_185:
	ds_read_u16 v73, v9 offset:0
	ds_read_u16 v74, v9 offset:512
	ds_read_u16 v75, v9 offset:1024
	ds_read_u16 v76, v9 offset:1536
	ds_read_u16 v77, v9 offset:2048
	ds_read_u16 v78, v9 offset:2560
	ds_read_u16 v79, v9 offset:3072
	ds_read_u16 v80, v9 offset:3584
	ds_read_u16 v81, v9 offset:4096
	ds_read_u16 v82, v9 offset:4608
	ds_read_u16 v83, v9 offset:5120
	ds_read_u16 v84, v9 offset:5632
	ds_read_u16 v85, v9 offset:6144
	ds_read_u16 v86, v9 offset:6656
	ds_read_u16 v87, v9 offset:7168
	s_waitcnt lgkmcnt(0)
	ds_read_u16 v88, v9 offset:7680
	ds_read_u16 v89, v9 offset:8192
	ds_read_u16 v90, v9 offset:8704
	ds_read_u16 v91, v9 offset:9216
	ds_read_u16 v92, v9 offset:9728
	ds_read_u16 v93, v9 offset:10240
	ds_read_u16 v94, v9 offset:10752
	ds_read_u16 v95, v9 offset:11264
	ds_read_u16 v96, v9 offset:11776
	ds_read_u16 v97, v9 offset:12288
	ds_read_u16 v98, v9 offset:12800
	ds_read_u16 v99, v9 offset:13312
	ds_read_u16 v100, v9 offset:13824
	ds_read_u16 v101, v9 offset:14336
	ds_read_u16 v102, v9 offset:14848
	s_waitcnt lgkmcnt(0)
	ds_read_u16 v103, v9 offset:15360
	ds_read_u16 v104, v9 offset:15872
	ds_read_u16 v105, v9 offset:16384
	ds_read_u16 v106, v9 offset:16896
	ds_read_u16 v107, v9 offset:17408
	ds_read_u16 v108, v9 offset:17920
	ds_read_u16 v109, v9 offset:18432
	ds_read_u16 v110, v9 offset:18944
	ds_read_u16 v111, v9 offset:19456
	ds_read_u16 v116, v9 offset:19968
	ds_read_u16 v117, v9 offset:20480
	ds_read_u16 v118, v9 offset:20992
	ds_read_u16 v119, v9 offset:21504
	ds_read_u16 v120, v9 offset:22016
	ds_read_u16 v121, v9 offset:22528
	s_waitcnt lgkmcnt(0)
	ds_read_u16 v122, v9 offset:23040
	s_waitcnt lgkmcnt(0)
	v_lshlrev_b32_e32 v73, 16, v73
	v_lshlrev_b32_e32 v74, 16, v74
	v_lshlrev_b32_e32 v75, 16, v75
	v_lshlrev_b32_e32 v76, 16, v76
	v_lshlrev_b32_e32 v77, 16, v77
	v_lshlrev_b32_e32 v78, 16, v78
	v_lshlrev_b32_e32 v79, 16, v79
	v_lshlrev_b32_e32 v80, 16, v80
	v_lshlrev_b32_e32 v81, 16, v81
	v_lshlrev_b32_e32 v82, 16, v82
	v_lshlrev_b32_e32 v83, 16, v83
	v_lshlrev_b32_e32 v84, 16, v84
	v_lshlrev_b32_e32 v85, 16, v85
	v_lshlrev_b32_e32 v86, 16, v86
	v_lshlrev_b32_e32 v87, 16, v87
	v_lshlrev_b32_e32 v88, 16, v88
	v_lshlrev_b32_e32 v89, 16, v89
	v_lshlrev_b32_e32 v90, 16, v90
	v_lshlrev_b32_e32 v91, 16, v91
	v_lshlrev_b32_e32 v92, 16, v92
	v_lshlrev_b32_e32 v93, 16, v93
	v_lshlrev_b32_e32 v94, 16, v94
	v_lshlrev_b32_e32 v95, 16, v95
	v_lshlrev_b32_e32 v96, 16, v96
	v_lshlrev_b32_e32 v97, 16, v97
	v_lshlrev_b32_e32 v98, 16, v98
	v_lshlrev_b32_e32 v99, 16, v99
	v_lshlrev_b32_e32 v100, 16, v100
	v_lshlrev_b32_e32 v101, 16, v101
	v_lshlrev_b32_e32 v102, 16, v102
	v_lshlrev_b32_e32 v103, 16, v103
	v_lshlrev_b32_e32 v104, 16, v104
	v_lshlrev_b32_e32 v105, 16, v105
	v_lshlrev_b32_e32 v106, 16, v106
	v_lshlrev_b32_e32 v107, 16, v107
	v_lshlrev_b32_e32 v108, 16, v108
	v_lshlrev_b32_e32 v109, 16, v109
	v_lshlrev_b32_e32 v110, 16, v110
	v_lshlrev_b32_e32 v111, 16, v111
	v_lshlrev_b32_e32 v116, 16, v116
	v_lshlrev_b32_e32 v117, 16, v117
	v_lshlrev_b32_e32 v118, 16, v118
	v_lshlrev_b32_e32 v119, 16, v119
	v_lshlrev_b32_e32 v120, 16, v120
	v_lshlrev_b32_e32 v121, 16, v121
	v_lshlrev_b32_e32 v122, 16, v122
	v_mov_b32_e32 v66, v64
	v_mov_b32_e32 v67, v65
	v_fmac_f32_e32 v66, v0, v73
	v_fmac_f32_e32 v67, v0, v74
	v_fmac_f32_e32 v66, v2, v74
	v_fmac_f32_e32 v67, v2, v75
	v_fmac_f32_e32 v66, v4, v75
	v_fmac_f32_e32 v67, v4, v76
	v_fmac_f32_e32 v66, v6, v76
	v_fmac_f32_e32 v67, v6, v77
	v_fmac_f32_e32 v66, v10, v77
	v_fmac_f32_e32 v67, v10, v78
	v_fmac_f32_e32 v66, v12, v78
	v_fmac_f32_e32 v67, v12, v79
	v_fmac_f32_e32 v66, v14, v79
	v_fmac_f32_e32 v67, v14, v80
	v_fmac_f32_e32 v66, v16, v80
	v_fmac_f32_e32 v67, v16, v81
	v_fmac_f32_e32 v66, v18, v81
	v_fmac_f32_e32 v67, v18, v82
	v_fmac_f32_e32 v66, v20, v82
	v_fmac_f32_e32 v67, v20, v83
	v_fmac_f32_e32 v66, v22, v83
	v_fmac_f32_e32 v67, v22, v84
	v_fmac_f32_e32 v66, v24, v84
	v_fmac_f32_e32 v67, v24, v85
	v_fmac_f32_e32 v66, v26, v85
	v_fmac_f32_e32 v67, v26, v86
	v_fmac_f32_e32 v66, v28, v86
	v_fmac_f32_e32 v67, v28, v87
	v_fmac_f32_e32 v66, v30, v87
	v_fmac_f32_e32 v67, v30, v88
	v_fmac_f32_e32 v66, v32, v88
	v_fmac_f32_e32 v67, v32, v89
	v_fmac_f32_e32 v66, v34, v89
	v_fmac_f32_e32 v67, v34, v90
	v_fmac_f32_e32 v66, v36, v90
	v_fmac_f32_e32 v67, v36, v91
	v_fmac_f32_e32 v66, v38, v91
	v_fmac_f32_e32 v67, v38, v92
	v_fmac_f32_e32 v66, v40, v92
	v_fmac_f32_e32 v67, v40, v93
	v_fmac_f32_e32 v66, v42, v93
	v_fmac_f32_e32 v67, v42, v94
	v_fmac_f32_e32 v66, v44, v94
	v_fmac_f32_e32 v67, v44, v95
	v_fmac_f32_e32 v66, v46, v95
	v_fmac_f32_e32 v67, v46, v96
	v_fmac_f32_e32 v66, v48, v96
	v_fmac_f32_e32 v67, v48, v97
	v_fmac_f32_e32 v66, v50, v97
	v_fmac_f32_e32 v67, v50, v98
	v_fmac_f32_e32 v66, v52, v98
	v_fmac_f32_e32 v67, v52, v99
	v_fmac_f32_e32 v66, v54, v99
	v_fmac_f32_e32 v67, v54, v100
	v_fmac_f32_e32 v66, v56, v100
	v_fmac_f32_e32 v67, v56, v101
	v_fmac_f32_e32 v66, v58, v101
	v_fmac_f32_e32 v67, v58, v102
	v_fmac_f32_e32 v66, v60, v102
	v_fmac_f32_e32 v67, v60, v103
	v_fmac_f32_e32 v66, v62, v103
	v_fmac_f32_e32 v67, v62, v104
	ds_write_b32 v68, v66 offset:23552
	ds_write_b32 v68, v67 offset:24576
	v_mov_b32_e32 v66, v64
	v_mov_b32_e32 v67, v65
	v_fmac_f32_e32 v66, v0, v75
	v_fmac_f32_e32 v67, v0, v76
	v_fmac_f32_e32 v66, v2, v76
	v_fmac_f32_e32 v67, v2, v77
	v_fmac_f32_e32 v66, v4, v77
	v_fmac_f32_e32 v67, v4, v78
	v_fmac_f32_e32 v66, v6, v78
	v_fmac_f32_e32 v67, v6, v79
	v_fmac_f32_e32 v66, v10, v79
	v_fmac_f32_e32 v67, v10, v80
	v_fmac_f32_e32 v66, v12, v80
	v_fmac_f32_e32 v67, v12, v81
	v_fmac_f32_e32 v66, v14, v81
	v_fmac_f32_e32 v67, v14, v82
	v_fmac_f32_e32 v66, v16, v82
; __device__ __forceinline__ float bf2f(bf16_t b) { return __uint_as_float(((unsigned)b) << 16); }
; __device__ void conv_item(const Params& p, int l, int item, char* smem) {
;     ...
;     for (int tl = 0; tl < 16; ++tl) {
;         float y = bias;
; #pragma unroll
;         for (int k = 0; k < 31; ++k) y += wk[k] * bf2f(sG[(tl + k) * 256 + tid]);
;         sY[tl * 256 + tid] = y;
;     }
	v_fmac_f32_e32 v67, v16, v83
	v_fmac_f32_e32 v66, v18, v83
	v_fmac_f32_e32 v67, v18, v84
	v_fmac_f32_e32 v66, v20, v84
	v_fmac_f32_e32 v67, v20, v85
	v_fmac_f32_e32 v66, v22, v85
	v_fmac_f32_e32 v67, v22, v86
	v_fmac_f32_e32 v66, v24, v86
	v_fmac_f32_e32 v67, v24, v87
	v_fmac_f32_e32 v66, v26, v87
	v_fmac_f32_e32 v67, v26, v88
	v_fmac_f32_e32 v66, v28, v88
	v_fmac_f32_e32 v67, v28, v89
	v_fmac_f32_e32 v66, v30, v89
	v_fmac_f32_e32 v67, v30, v90
	v_fmac_f32_e32 v66, v32, v90
	v_fmac_f32_e32 v67, v32, v91
	v_fmac_f32_e32 v66, v34, v91
	v_fmac_f32_e32 v67, v34, v92
	v_fmac_f32_e32 v66, v36, v92
	v_fmac_f32_e32 v67, v36, v93
	v_fmac_f32_e32 v66, v38, v93
	v_fmac_f32_e32 v67, v38, v94
	v_fmac_f32_e32 v66, v40, v94
	v_fmac_f32_e32 v67, v40, v95
	v_fmac_f32_e32 v66, v42, v95
	v_fmac_f32_e32 v67, v42, v96
	v_fmac_f32_e32 v66, v44, v96
	v_fmac_f32_e32 v67, v44, v97
	v_fmac_f32_e32 v66, v46, v97
	v_fmac_f32_e32 v67, v46, v98
	v_fmac_f32_e32 v66, v48, v98
	v_fmac_f32_e32 v67, v48, v99
	v_fmac_f32_e32 v66, v50, v99
	v_fmac_f32_e32 v67, v50, v100
	v_fmac_f32_e32 v66, v52, v100
	v_fmac_f32_e32 v67, v52, v101
	v_fmac_f32_e32 v66, v54, v101
	v_fmac_f32_e32 v67, v54, v102
	v_fmac_f32_e32 v66, v56, v102
	v_fmac_f32_e32 v67, v56, v103
	v_fmac_f32_e32 v66, v58, v103
	v_fmac_f32_e32 v67, v58, v104
	v_fmac_f32_e32 v66, v60, v104
	v_fmac_f32_e32 v67, v60, v105
	v_fmac_f32_e32 v66, v62, v105
	v_fmac_f32_e32 v67, v62, v106
	ds_write_b32 v68, v66 offset:25600
	ds_write_b32 v68, v67 offset:26624
	v_mov_b32_e32 v66, v64
	v_mov_b32_e32 v67, v65
	v_fmac_f32_e32 v66, v0, v77
	v_fmac_f32_e32 v67, v0, v78
	v_fmac_f32_e32 v66, v2, v78
	v_fmac_f32_e32 v67, v2, v79
	v_fmac_f32_e32 v66, v4, v79
	v_fmac_f32_e32 v67, v4, v80
	v_fmac_f32_e32 v66, v6, v80
	v_fmac_f32_e32 v67, v6, v81
	v_fmac_f32_e32 v66, v10, v81
	v_fmac_f32_e32 v67, v10, v82
	v_fmac_f32_e32 v66, v12, v82
	v_fmac_f32_e32 v67, v12, v83
	v_fmac_f32_e32 v66, v14, v83
	v_fmac_f32_e32 v67, v14, v84
	v_fmac_f32_e32 v66, v16, v84
	v_fmac_f32_e32 v67, v16, v85
	v_fmac_f32_e32 v66, v18, v85
	v_fmac_f32_e32 v67, v18, v86
	v_fmac_f32_e32 v66, v20, v86
	v_fmac_f32_e32 v67, v20, v87
	v_fmac_f32_e32 v66, v22, v87
	v_fmac_f32_e32 v67, v22, v88
	v_fmac_f32_e32 v66, v24, v88
	v_fmac_f32_e32 v67, v24, v89
	v_fmac_f32_e32 v66, v26, v89
	v_fmac_f32_e32 v67, v26, v90
	v_fmac_f32_e32 v66, v28, v90
	v_fmac_f32_e32 v67, v28, v91
	v_fmac_f32_e32 v66, v30, v91
	v_fmac_f32_e32 v67, v30, v92
	v_fmac_f32_e32 v66, v32, v92
	v_fmac_f32_e32 v67, v32, v93
	v_fmac_f32_e32 v66, v34, v93
	v_fmac_f32_e32 v67, v34, v94
	v_fmac_f32_e32 v66, v36, v94
	v_fmac_f32_e32 v67, v36, v95
	v_fmac_f32_e32 v66, v38, v95
	v_fmac_f32_e32 v67, v38, v96
	v_fmac_f32_e32 v66, v40, v96
	v_fmac_f32_e32 v67, v40, v97
	v_fmac_f32_e32 v66, v42, v97
	v_fmac_f32_e32 v67, v42, v98
	v_fmac_f32_e32 v66, v44, v98
	v_fmac_f32_e32 v67, v44, v99
	v_fmac_f32_e32 v66, v46, v99
	v_fmac_f32_e32 v67, v46, v100
	v_fmac_f32_e32 v66, v48, v100
	v_fmac_f32_e32 v67, v48, v101
	v_fmac_f32_e32 v66, v50, v101
	v_fmac_f32_e32 v67, v50, v102
	v_fmac_f32_e32 v66, v52, v102
	v_fmac_f32_e32 v67, v52, v103
	v_fmac_f32_e32 v66, v54, v103
	v_fmac_f32_e32 v67, v54, v104
	v_fmac_f32_e32 v66, v56, v104
	v_fmac_f32_e32 v67, v56, v105
	v_fmac_f32_e32 v66, v58, v105
	v_fmac_f32_e32 v67, v58, v106
	v_fmac_f32_e32 v66, v60, v106
	v_fmac_f32_e32 v67, v60, v107
	v_fmac_f32_e32 v66, v62, v107
	v_fmac_f32_e32 v67, v62, v108
	ds_write_b32 v68, v66 offset:27648
	ds_write_b32 v68, v67 offset:28672
	v_mov_b32_e32 v66, v64
	v_mov_b32_e32 v67, v65
	v_fmac_f32_e32 v66, v0, v79
	v_fmac_f32_e32 v67, v0, v80
	v_fmac_f32_e32 v66, v2, v80
	v_fmac_f32_e32 v67, v2, v81
	v_fmac_f32_e32 v66, v4, v81
	v_fmac_f32_e32 v67, v4, v82
	v_fmac_f32_e32 v66, v6, v82
	v_fmac_f32_e32 v67, v6, v83
	v_fmac_f32_e32 v66, v10, v83
	v_fmac_f32_e32 v67, v10, v84
	v_fmac_f32_e32 v66, v12, v84
	v_fmac_f32_e32 v67, v12, v85
	v_fmac_f32_e32 v66, v14, v85
	v_fmac_f32_e32 v67, v14, v86
	v_fmac_f32_e32 v66, v16, v86
	v_fmac_f32_e32 v67, v16, v87
	v_fmac_f32_e32 v66, v18, v87
	v_fmac_f32_e32 v67, v18, v88
	v_fmac_f32_e32 v66, v20, v88
	v_fmac_f32_e32 v67, v20, v89
	v_fmac_f32_e32 v66, v22, v89
	v_fmac_f32_e32 v67, v22, v90
	v_fmac_f32_e32 v66, v24, v90
	v_fmac_f32_e32 v67, v24, v91
	v_fmac_f32_e32 v66, v26, v91
	v_fmac_f32_e32 v67, v26, v92
	v_fmac_f32_e32 v66, v28, v92
	v_fmac_f32_e32 v67, v28, v93
	v_fmac_f32_e32 v66, v30, v93
	v_fmac_f32_e32 v67, v30, v94
	v_fmac_f32_e32 v66, v32, v94
	v_fmac_f32_e32 v67, v32, v95
	v_fmac_f32_e32 v66, v34, v95
	v_fmac_f32_e32 v67, v34, v96
	v_fmac_f32_e32 v66, v36, v96
	v_fmac_f32_e32 v67, v36, v97
	v_fmac_f32_e32 v66, v38, v97
	v_fmac_f32_e32 v67, v38, v98
	v_fmac_f32_e32 v66, v40, v98
	v_fmac_f32_e32 v67, v40, v99
	v_fmac_f32_e32 v66, v42, v99
	v_fmac_f32_e32 v67, v42, v100
	v_fmac_f32_e32 v66, v44, v100
	v_fmac_f32_e32 v67, v44, v101
	v_fmac_f32_e32 v66, v46, v101
	v_fmac_f32_e32 v67, v46, v102
	v_fmac_f32_e32 v66, v48, v102
	v_fmac_f32_e32 v67, v48, v103
	v_fmac_f32_e32 v66, v50, v103
	v_fmac_f32_e32 v67, v50, v104
	v_fmac_f32_e32 v66, v52, v104
	v_fmac_f32_e32 v67, v52, v105
	v_fmac_f32_e32 v66, v54, v105
	v_fmac_f32_e32 v67, v54, v106
	v_fmac_f32_e32 v66, v56, v106
	v_fmac_f32_e32 v67, v56, v107
	v_fmac_f32_e32 v66, v58, v107
	v_fmac_f32_e32 v67, v58, v108
	v_fmac_f32_e32 v66, v60, v108
	v_fmac_f32_e32 v67, v60, v109
	v_fmac_f32_e32 v66, v62, v109
	v_fmac_f32_e32 v67, v62, v110
	ds_write_b32 v68, v66 offset:29696
	ds_write_b32 v68, v67 offset:30720
	v_mov_b32_e32 v66, v64
	v_mov_b32_e32 v67, v65
	v_fmac_f32_e32 v66, v0, v81
	v_fmac_f32_e32 v67, v0, v82
	v_fmac_f32_e32 v66, v2, v82
	v_fmac_f32_e32 v67, v2, v83
; __device__ __forceinline__ float bf2f(bf16_t b) { return __uint_as_float(((unsigned)b) << 16); }
; __device__ void conv_item(const Params& p, int l, int item, char* smem) {
;     ...
;     for (int tl = 0; tl < 16; ++tl) {
;         float y = bias;
; #pragma unroll
;         for (int k = 0; k < 31; ++k) y += wk[k] * bf2f(sG[(tl + k) * 256 + tid]);
;         sY[tl * 256 + tid] = y;
;     }
	v_fmac_f32_e32 v66, v4, v83
	v_fmac_f32_e32 v67, v4, v84
	v_fmac_f32_e32 v66, v6, v84
	v_fmac_f32_e32 v67, v6, v85
	v_fmac_f32_e32 v66, v10, v85
	v_fmac_f32_e32 v67, v10, v86
	v_fmac_f32_e32 v66, v12, v86
	v_fmac_f32_e32 v67, v12, v87
	v_fmac_f32_e32 v66, v14, v87
	v_fmac_f32_e32 v67, v14, v88
	v_fmac_f32_e32 v66, v16, v88
	v_fmac_f32_e32 v67, v16, v89
	v_fmac_f32_e32 v66, v18, v89
	v_fmac_f32_e32 v67, v18, v90
	v_fmac_f32_e32 v66, v20, v90
	v_fmac_f32_e32 v67, v20, v91
	v_fmac_f32_e32 v66, v22, v91
	v_fmac_f32_e32 v67, v22, v92
	v_fmac_f32_e32 v66, v24, v92
	v_fmac_f32_e32 v67, v24, v93
	v_fmac_f32_e32 v66, v26, v93
	v_fmac_f32_e32 v67, v26, v94
	v_fmac_f32_e32 v66, v28, v94
	v_fmac_f32_e32 v67, v28, v95
	v_fmac_f32_e32 v66, v30, v95
	v_fmac_f32_e32 v67, v30, v96
	v_fmac_f32_e32 v66, v32, v96
	v_fmac_f32_e32 v67, v32, v97
	v_fmac_f32_e32 v66, v34, v97
	v_fmac_f32_e32 v67, v34, v98
	v_fmac_f32_e32 v66, v36, v98
	v_fmac_f32_e32 v67, v36, v99
	v_fmac_f32_e32 v66, v38, v99
	v_fmac_f32_e32 v67, v38, v100
	v_fmac_f32_e32 v66, v40, v100
	v_fmac_f32_e32 v67, v40, v101
	v_fmac_f32_e32 v66, v42, v101
	v_fmac_f32_e32 v67, v42, v102
	v_fmac_f32_e32 v66, v44, v102
	v_fmac_f32_e32 v67, v44, v103
	v_fmac_f32_e32 v66, v46, v103
	v_fmac_f32_e32 v67, v46, v104
	v_fmac_f32_e32 v66, v48, v104
	v_fmac_f32_e32 v67, v48, v105
	v_fmac_f32_e32 v66, v50, v105
	v_fmac_f32_e32 v67, v50, v106
	v_fmac_f32_e32 v66, v52, v106
	v_fmac_f32_e32 v67, v52, v107
	v_fmac_f32_e32 v66, v54, v107
	v_fmac_f32_e32 v67, v54, v108
	v_fmac_f32_e32 v66, v56, v108
	v_fmac_f32_e32 v67, v56, v109
	v_fmac_f32_e32 v66, v58, v109
	v_fmac_f32_e32 v67, v58, v110
	v_fmac_f32_e32 v66, v60, v110
	v_fmac_f32_e32 v67, v60, v111
	v_fmac_f32_e32 v66, v62, v111
	v_fmac_f32_e32 v67, v62, v116
	ds_write_b32 v68, v66 offset:31744
	ds_write_b32 v68, v67 offset:32768
	v_mov_b32_e32 v66, v64
	v_mov_b32_e32 v67, v65
	v_fmac_f32_e32 v66, v0, v83
	v_fmac_f32_e32 v67, v0, v84
	v_fmac_f32_e32 v66, v2, v84
	v_fmac_f32_e32 v67, v2, v85
	v_fmac_f32_e32 v66, v4, v85
	v_fmac_f32_e32 v67, v4, v86
	v_fmac_f32_e32 v66, v6, v86
	v_fmac_f32_e32 v67, v6, v87
	v_fmac_f32_e32 v66, v10, v87
	v_fmac_f32_e32 v67, v10, v88
	v_fmac_f32_e32 v66, v12, v88
	v_fmac_f32_e32 v67, v12, v89
	v_fmac_f32_e32 v66, v14, v89
	v_fmac_f32_e32 v67, v14, v90
	v_fmac_f32_e32 v66, v16, v90
	v_fmac_f32_e32 v67, v16, v91
	v_fmac_f32_e32 v66, v18, v91
	v_fmac_f32_e32 v67, v18, v92
	v_fmac_f32_e32 v66, v20, v92
	v_fmac_f32_e32 v67, v20, v93
	v_fmac_f32_e32 v66, v22, v93
	v_fmac_f32_e32 v67, v22, v94
	v_fmac_f32_e32 v66, v24, v94
	v_fmac_f32_e32 v67, v24, v95
	v_fmac_f32_e32 v66, v26, v95
	v_fmac_f32_e32 v67, v26, v96
	v_fmac_f32_e32 v66, v28, v96
	v_fmac_f32_e32 v67, v28, v97
	v_fmac_f32_e32 v66, v30, v97
	v_fmac_f32_e32 v67, v30, v98
	v_fmac_f32_e32 v66, v32, v98
	v_fmac_f32_e32 v67, v32, v99
	v_fmac_f32_e32 v66, v34, v99
	v_fmac_f32_e32 v67, v34, v100
	v_fmac_f32_e32 v66, v36, v100
	v_fmac_f32_e32 v67, v36, v101
	v_fmac_f32_e32 v66, v38, v101
	v_fmac_f32_e32 v67, v38, v102
	v_fmac_f32_e32 v66, v40, v102
	v_fmac_f32_e32 v67, v40, v103
	v_fmac_f32_e32 v66, v42, v103
	v_fmac_f32_e32 v67, v42, v104
	v_fmac_f32_e32 v66, v44, v104
	v_fmac_f32_e32 v67, v44, v105
	v_fmac_f32_e32 v66, v46, v105
	v_fmac_f32_e32 v67, v46, v106
	v_fmac_f32_e32 v66, v48, v106
	v_fmac_f32_e32 v67, v48, v107
	v_fmac_f32_e32 v66, v50, v107
	v_fmac_f32_e32 v67, v50, v108
	v_fmac_f32_e32 v66, v52, v108
	v_fmac_f32_e32 v67, v52, v109
	v_fmac_f32_e32 v66, v54, v109
	v_fmac_f32_e32 v67, v54, v110
	v_fmac_f32_e32 v66, v56, v110
	v_fmac_f32_e32 v67, v56, v111
	v_fmac_f32_e32 v66, v58, v111
	v_fmac_f32_e32 v67, v58, v116
	v_fmac_f32_e32 v66, v60, v116
	v_fmac_f32_e32 v67, v60, v117
	v_fmac_f32_e32 v66, v62, v117
	v_fmac_f32_e32 v67, v62, v118
	ds_write_b32 v68, v66 offset:33792
	ds_write_b32 v68, v67 offset:34816
	v_mov_b32_e32 v66, v64
	v_mov_b32_e32 v67, v65
	v_fmac_f32_e32 v66, v0, v85
	v_fmac_f32_e32 v67, v0, v86
	v_fmac_f32_e32 v66, v2, v86
	v_fmac_f32_e32 v67, v2, v87
	v_fmac_f32_e32 v66, v4, v87
	v_fmac_f32_e32 v67, v4, v88
	v_fmac_f32_e32 v66, v6, v88
	v_fmac_f32_e32 v67, v6, v89
	v_fmac_f32_e32 v66, v10, v89
	v_fmac_f32_e32 v67, v10, v90
	v_fmac_f32_e32 v66, v12, v90
	v_fmac_f32_e32 v67, v12, v91
	v_fmac_f32_e32 v66, v14, v91
	v_fmac_f32_e32 v67, v14, v92
	v_fmac_f32_e32 v66, v16, v92
	v_fmac_f32_e32 v67, v16, v93
	v_fmac_f32_e32 v66, v18, v93
	v_fmac_f32_e32 v67, v18, v94
	v_fmac_f32_e32 v66, v20, v94
	v_fmac_f32_e32 v67, v20, v95
	v_fmac_f32_e32 v66, v22, v95
	v_fmac_f32_e32 v67, v22, v96
	v_fmac_f32_e32 v66, v24, v96
	v_fmac_f32_e32 v67, v24, v97
	v_fmac_f32_e32 v66, v26, v97
	v_fmac_f32_e32 v67, v26, v98
	v_fmac_f32_e32 v66, v28, v98
	v_fmac_f32_e32 v67, v28, v99
	v_fmac_f32_e32 v66, v30, v99
	v_fmac_f32_e32 v67, v30, v100
	v_fmac_f32_e32 v66, v32, v100
	v_fmac_f32_e32 v67, v32, v101
	v_fmac_f32_e32 v66, v34, v101
	v_fmac_f32_e32 v67, v34, v102
	v_fmac_f32_e32 v66, v36, v102
	v_fmac_f32_e32 v67, v36, v103
	v_fmac_f32_e32 v66, v38, v103
	v_fmac_f32_e32 v67, v38, v104
	v_fmac_f32_e32 v66, v40, v104
	v_fmac_f32_e32 v67, v40, v105
	v_fmac_f32_e32 v66, v42, v105
	v_fmac_f32_e32 v67, v42, v106
	v_fmac_f32_e32 v66, v44, v106
	v_fmac_f32_e32 v67, v44, v107
	v_fmac_f32_e32 v66, v46, v107
	v_fmac_f32_e32 v67, v46, v108
	v_fmac_f32_e32 v66, v48, v108
	v_fmac_f32_e32 v67, v48, v109
	v_fmac_f32_e32 v66, v50, v109
	v_fmac_f32_e32 v67, v50, v110
	v_fmac_f32_e32 v66, v52, v110
	v_fmac_f32_e32 v67, v52, v111
	v_fmac_f32_e32 v66, v54, v111
	v_fmac_f32_e32 v67, v54, v116
	v_fmac_f32_e32 v66, v56, v116
	v_fmac_f32_e32 v67, v56, v117
	v_fmac_f32_e32 v66, v58, v117
	v_fmac_f32_e32 v67, v58, v118
; __device__ __forceinline__ float bf2f(bf16_t b) { return __uint_as_float(((unsigned)b) << 16); }
; __device__ void conv_item(const Params& p, int l, int item, char* smem) {
;     ...
;     for (int tl = 0; tl < 16; ++tl) {
;         float y = bias;
; #pragma unroll
;         for (int k = 0; k < 31; ++k) y += wk[k] * bf2f(sG[(tl + k) * 256 + tid]);
;         sY[tl * 256 + tid] = y;
;     }
;     __syncthreads();
;     const float4 g4 = *(const float4*)(p.ln_g + l * 256 + lane * 4), b4 = *(const float4*)(p.ln_b + l * 256 + lane * 4);
; #pragma unroll
;     for (int j = 0; j < 4; ++j) {
;         const int tl = wid * 4 + j;
;         const float4 y = *(const float4*)(sY + tl * 256 + lane * 4);
;         const float s1 = wave_sum(y.x + y.y + y.z + y.w);
;         const float mean = s1 * (1.0f / 256.0f);
;         const float dx = y.x - mean, dy = y.y - mean, dz = y.z - mean, dw = y.w - mean;
;         const float s2 = wave_sum(dx * dx + dy * dy + dz * dz + dw * dw);
;         const float rstd = rsqrtf(s2 * (1.0f / 256.0f) + EPS);
;         float o0 = dx * rstd * g4.x + b4.x, o1 = dy * rstd * g4.y + b4.y, o2 = dz * rstd * g4.z + b4.z, o3 = dw * rstd * g4.w + b4.w;
	v_fmac_f32_e32 v66, v60, v118
	v_fmac_f32_e32 v67, v60, v119
	v_fmac_f32_e32 v66, v62, v119
	v_fmac_f32_e32 v67, v62, v120
	ds_write_b32 v68, v66 offset:35840
	ds_write_b32 v68, v67 offset:36864
	v_mov_b32_e32 v66, v64
	v_mov_b32_e32 v67, v65
	v_fmac_f32_e32 v66, v0, v87
	v_fmac_f32_e32 v67, v0, v88
	v_fmac_f32_e32 v66, v2, v88
	v_fmac_f32_e32 v67, v2, v89
	v_fmac_f32_e32 v66, v4, v89
	v_fmac_f32_e32 v67, v4, v90
	v_fmac_f32_e32 v66, v6, v90
	v_fmac_f32_e32 v67, v6, v91
	v_fmac_f32_e32 v66, v10, v91
	v_fmac_f32_e32 v67, v10, v92
	v_fmac_f32_e32 v66, v12, v92
	v_fmac_f32_e32 v67, v12, v93
	v_fmac_f32_e32 v66, v14, v93
	v_fmac_f32_e32 v67, v14, v94
	v_fmac_f32_e32 v66, v16, v94
	v_fmac_f32_e32 v67, v16, v95
	v_fmac_f32_e32 v66, v18, v95
	v_fmac_f32_e32 v67, v18, v96
	v_fmac_f32_e32 v66, v20, v96
	v_fmac_f32_e32 v67, v20, v97
	v_fmac_f32_e32 v66, v22, v97
	v_fmac_f32_e32 v67, v22, v98
	v_fmac_f32_e32 v66, v24, v98
	v_fmac_f32_e32 v67, v24, v99
	v_fmac_f32_e32 v66, v26, v99
	v_fmac_f32_e32 v67, v26, v100
	v_fmac_f32_e32 v66, v28, v100
	v_fmac_f32_e32 v67, v28, v101
	v_fmac_f32_e32 v66, v30, v101
	v_fmac_f32_e32 v67, v30, v102
	v_fmac_f32_e32 v66, v32, v102
	v_fmac_f32_e32 v67, v32, v103
	v_fmac_f32_e32 v66, v34, v103
	v_fmac_f32_e32 v67, v34, v104
	v_fmac_f32_e32 v66, v36, v104
	v_fmac_f32_e32 v67, v36, v105
	v_fmac_f32_e32 v66, v38, v105
	v_fmac_f32_e32 v67, v38, v106
	v_fmac_f32_e32 v66, v40, v106
	v_fmac_f32_e32 v67, v40, v107
	v_fmac_f32_e32 v66, v42, v107
	v_fmac_f32_e32 v67, v42, v108
	v_fmac_f32_e32 v66, v44, v108
	v_fmac_f32_e32 v67, v44, v109
	v_fmac_f32_e32 v66, v46, v109
	v_fmac_f32_e32 v67, v46, v110
	v_fmac_f32_e32 v66, v48, v110
	v_fmac_f32_e32 v67, v48, v111
	v_fmac_f32_e32 v66, v50, v111
	v_fmac_f32_e32 v67, v50, v116
	v_fmac_f32_e32 v66, v52, v116
	v_fmac_f32_e32 v67, v52, v117
	v_fmac_f32_e32 v66, v54, v117
	v_fmac_f32_e32 v67, v54, v118
	v_fmac_f32_e32 v66, v56, v118
	v_fmac_f32_e32 v67, v56, v119
	v_fmac_f32_e32 v66, v58, v119
	v_fmac_f32_e32 v67, v58, v120
	v_fmac_f32_e32 v66, v60, v120
	v_fmac_f32_e32 v67, v60, v121
	v_fmac_f32_e32 v66, v62, v121
	v_fmac_f32_e32 v67, v62, v122
	ds_write_b32 v68, v66 offset:37888
	ds_write_b32 v68, v67 offset:38912
	s_mov_b32 s12, 16
	s_mov_b32 s13, 17
	s_mov_b32 s14, 0
	v_cmp_lt_i32_e32 vcc, v133, v132
	v_lshlrev_b32_e32 v0, 2, v8
	v_ashrrev_i32_e32 v23, 4, v8
	v_cndmask_b32_e32 v8, v130, v133, vcc
	v_cmp_lt_i32_e32 vcc, v134, v132
	v_lshlrev_b32_e32 v21, 2, v8
	v_and_b32_e32 v26, 0xfc, v0
	v_cndmask_b32_e32 v8, v130, v134, vcc
	v_cmp_lt_i32_e32 vcc, v125, v132
	v_lshlrev_b32_e32 v20, 2, v8
	v_lshlrev_b32_e32 v22, 2, v26
	v_cndmask_b32_e32 v8, v130, v125, vcc
	v_cmp_lt_i32_e32 vcc, v127, v132
	v_lshlrev_b32_e32 v19, 2, v8
	v_and_b32_e32 v12, -4, v23
	v_cndmask_b32_e32 v8, v130, v127, vcc
	v_cmp_lt_i32_e32 vcc, v128, v132
	v_lshlrev_b32_e32 v18, 2, v8
	s_waitcnt lgkmcnt(0)
	v_cndmask_b32_e32 v8, v130, v128, vcc
	v_cmp_lt_i32_e32 vcc, v129, v132
	v_lshlrev_b32_e32 v17, 2, v8
	s_barrier
	v_cndmask_b32_e32 v8, v130, v129, vcc
	v_lshlrev_b32_e32 v16, 2, v8
	v_lshl_or_b32 v8, v12, 10, v22
	global_load_dwordx4 v[4:7], v22, s[40:41]
	global_load_dwordx4 v[0:3], v22, s[42:43]
	ds_read_b128 v[8:11], v8 offset:23552
	s_lshl_b64 s[34:35], s[46:47], 13
	v_mov_b32_e32 v28, 0x358637bd
	s_or_b32 s34, s34, s1
	s_mov_b32 s1, 0x800000
	s_waitcnt lgkmcnt(0)
	v_add_f32_e32 v13, v8, v9
	v_add_f32_e32 v13, v13, v10
	v_add_f32_e32 v13, v13, v11
	ds_bpermute_b32 v14, v21, v13
	v_readlane_b32 s14, v165, 8
	v_readlane_b32 s15, v165, 9
	v_lshlrev_b32_e32 v112, 1, v26
	s_add_i32 s11, s11, s10
	s_waitcnt lgkmcnt(0)
	v_add_f32_e32 v13, v13, v14
	ds_bpermute_b32 v14, v20, v13
	v_readlane_b32 s68, v167, 17
	s_mov_b32 s7, 0x800000
	s_cmpk_gt_i32 s11, 0x7ff
	v_readlane_b32 s69, v167, 18
	s_waitcnt lgkmcnt(0)
	v_add_f32_e32 v13, v13, v14
	ds_bpermute_b32 v14, v19, v13
	v_readlane_b32 s70, v167, 19
	v_readlane_b32 s71, v167, 20
	v_readlane_b32 s72, v167, 21
	v_readlane_b32 s73, v167, 22
	s_waitcnt lgkmcnt(0)
	v_add_f32_e32 v13, v13, v14
	ds_bpermute_b32 v14, v18, v13
	v_readlane_b32 s74, v167, 23
	v_readlane_b32 s75, v167, 24
	v_readlane_b32 s76, v167, 25
	v_readlane_b32 s77, v167, 26
	s_waitcnt lgkmcnt(0)
	v_add_f32_e32 v13, v13, v14
	ds_bpermute_b32 v14, v17, v13
	v_readlane_b32 s78, v167, 27
	v_readlane_b32 s79, v167, 28
	v_readlane_b32 s80, v167, 29
	v_readlane_b32 s81, v167, 30
	s_waitcnt lgkmcnt(0)
	v_add_f32_e32 v13, v13, v14
	ds_bpermute_b32 v14, v16, v13
	v_readlane_b32 s82, v167, 31
	v_readlane_b32 s83, v167, 32
	s_waitcnt lgkmcnt(0)
	v_add_f32_e32 v13, v13, v14
	v_mul_f32_e32 v14, 0x3b800000, v13
	v_pk_add_f32 v[8:9], v[8:9], v[14:15] op_sel_hi:[1,0] neg_lo:[0,1] neg_hi:[0,1]
	v_pk_add_f32 v[10:11], v[10:11], v[14:15] op_sel_hi:[1,0] neg_lo:[0,1] neg_hi:[0,1]
	v_pk_mul_f32 v[14:15], v[8:9], v[8:9]
	v_pk_mul_f32 v[24:25], v[10:11], v[10:11]
	v_add_f32_e32 v13, v14, v15
	v_add_f32_e32 v13, v24, v13
	v_add_f32_e32 v13, v25, v13
	ds_bpermute_b32 v14, v21, v13
	s_waitcnt lgkmcnt(0)
	v_add_f32_e32 v13, v13, v14
	ds_bpermute_b32 v14, v20, v13
	s_waitcnt lgkmcnt(0)
	v_add_f32_e32 v13, v13, v14
	ds_bpermute_b32 v14, v19, v13
	s_waitcnt lgkmcnt(0)
	v_add_f32_e32 v13, v13, v14
	ds_bpermute_b32 v14, v18, v13
	s_waitcnt lgkmcnt(0)
	v_add_f32_e32 v13, v13, v14
	ds_bpermute_b32 v14, v17, v13
	s_waitcnt lgkmcnt(0)
	v_add_f32_e32 v13, v13, v14
	ds_bpermute_b32 v14, v16, v13
	s_waitcnt lgkmcnt(0)
	v_add_f32_e32 v13, v13, v14
	v_fmamk_f32 v13, v13, 0x3b800000, v28
	v_cmp_gt_f32_e32 vcc, s1, v13
	v_mul_f32_e32 v14, 0x4b800000, v13
	s_nop 0
	v_cndmask_b32_e32 v13, v13, v14, vcc
	v_rsq_f32_e32 v13, v13
	s_nop 0
	v_mul_f32_e32 v14, 0x45800000, v13
	v_cndmask_b32_e32 v13, v13, v14, vcc
	v_mul_f32_e32 v8, v8, v13
	s_waitcnt vmcnt(0)
; __device__ __forceinline__ unsigned pk_bf16(float lo, float hi) { unsigned r; asm("v_cvt_pk_bf16_f32 %0, %1, %2" : "=v"(r) : "v"(lo), "v"(hi)); return r; }
; __device__ __forceinline__ float sigmoidf_(float x) { return 1.0f / (1.0f + __expf(-x)); }
; __device__ void conv_item(const Params& p, int l, int item, char* smem) {
;     ...
;         const float4 y = *(const float4*)(sY + tl * 256 + lane * 4);
;         const float s1 = wave_sum(y.x + y.y + y.z + y.w);
;         const float mean = s1 * (1.0f / 256.0f);
;         const float dx = y.x - mean, dy = y.y - mean, dz = y.z - mean, dw = y.w - mean;
;         const float s2 = wave_sum(dx * dx + dy * dy + dz * dz + dw * dw);
;         const float rstd = rsqrtf(s2 * (1.0f / 256.0f) + EPS);
;         float o0 = dx * rstd * g4.x + b4.x, o1 = dy * rstd * g4.y + b4.y, o2 = dz * rstd * g4.z + b4.z, o3 = dw * rstd * g4.w + b4.w;
;         o0 *= sigmoidf_(o0); o1 *= sigmoidf_(o1); o2 *= sigmoidf_(o2); o3 *= sigmoidf_(o3);
;         uint2 w; w.x = pk_bf16(o0, o1); w.y = pk_bf16(o2, o3);
;         *(uint2*)(p.mixed + ((size_t)b * S + t0 + tl) * 1024 + 512 + lane * 4) = w;
	v_fma_f32 v8, v4, v8, v0
	v_mul_f32_e32 v9, v9, v13
	v_mul_f32_e32 v10, v10, v13
	v_mul_f32_e32 v11, v11, v13
	v_mul_f32_e32 v13, 0xbfb8aa3b, v8
	v_exp_f32_e32 v13, v13
	v_fma_f32 v9, v5, v9, v1
	v_fma_f32 v10, v6, v10, v2
	v_fma_f32 v11, v7, v11, v3
	v_add_f32_e32 v13, 1.0, v13
	v_div_scale_f32 v14, s[12:13], v13, v13, 1.0
	v_rcp_f32_e32 v15, v14
	s_nop 0
	v_fma_f32 v24, -v14, v15, 1.0
	v_fmac_f32_e32 v15, v24, v15
	v_div_scale_f32 v24, vcc, 1.0, v13, 1.0
	v_mul_f32_e32 v25, v24, v15
	v_fma_f32 v27, -v14, v25, v24
	v_fmac_f32_e32 v25, v27, v15
	v_fma_f32 v14, -v14, v25, v24
	v_div_fmas_f32 v14, v14, v15, v25
	v_div_fixup_f32 v13, v14, v13, 1.0
	v_mul_f32_e32 v8, v8, v13
	v_mul_f32_e32 v13, 0xbfb8aa3b, v9
	v_exp_f32_e32 v13, v13
	s_nop 0
	v_add_f32_e32 v13, 1.0, v13
	v_div_scale_f32 v14, s[12:13], v13, v13, 1.0
	v_rcp_f32_e32 v15, v14
	s_nop 0
	v_fma_f32 v24, -v14, v15, 1.0
	v_fmac_f32_e32 v15, v24, v15
	v_div_scale_f32 v24, vcc, 1.0, v13, 1.0
	v_mul_f32_e32 v25, v24, v15
	v_fma_f32 v27, -v14, v25, v24
	v_fmac_f32_e32 v25, v27, v15
	v_fma_f32 v14, -v14, v25, v24
	v_div_fmas_f32 v14, v14, v15, v25
	v_div_fixup_f32 v13, v14, v13, 1.0
	v_mul_f32_e32 v9, v9, v13
	v_mul_f32_e32 v13, 0xbfb8aa3b, v10
	v_exp_f32_e32 v13, v13
	v_cvt_pk_bf16_f32 v8, v8, v9
	s_nop 0
	v_add_f32_e32 v13, 1.0, v13
	v_div_scale_f32 v14, s[12:13], v13, v13, 1.0
	v_rcp_f32_e32 v15, v14
	s_nop 0
	v_fma_f32 v24, -v14, v15, 1.0
	v_fmac_f32_e32 v15, v24, v15
	v_div_scale_f32 v24, vcc, 1.0, v13, 1.0
	v_mul_f32_e32 v25, v24, v15
	v_fma_f32 v27, -v14, v25, v24
	v_fmac_f32_e32 v25, v27, v15
	v_fma_f32 v14, -v14, v25, v24
	v_div_fmas_f32 v14, v14, v15, v25
	v_div_fixup_f32 v13, v14, v13, 1.0
	v_mul_f32_e32 v10, v10, v13
	v_mul_f32_e32 v13, 0xbfb8aa3b, v11
	v_exp_f32_e32 v13, v13
	s_nop 0
	v_add_f32_e32 v13, 1.0, v13
	v_div_scale_f32 v14, s[12:13], v13, v13, 1.0
	v_rcp_f32_e32 v15, v14
	s_nop 0
	v_fma_f32 v24, -v14, v15, 1.0
	v_fmac_f32_e32 v15, v24, v15
	v_div_scale_f32 v24, vcc, 1.0, v13, 1.0
	v_mul_f32_e32 v25, v24, v15
	v_fma_f32 v27, -v14, v25, v24
	v_fmac_f32_e32 v25, v27, v15
	v_fma_f32 v14, -v14, v25, v24
	v_div_fmas_f32 v14, v14, v15, v25
	v_div_fixup_f32 v13, v14, v13, 1.0
	v_mul_f32_e32 v11, v11, v13
	v_ashrrev_i32_e32 v13, 31, v12
	v_cvt_pk_bf16_f32 v9, v10, v11
	v_lshl_add_u64 v[10:11], s[34:35], 0, v[12:13]
	v_lshlrev_b64 v[10:11], 11, v[10:11]
	v_lshl_add_u64 v[10:11], s[14:15], 0, v[10:11]
	v_lshl_add_u64 v[10:11], v[10:11], 0, v[112:113]
	v_or_b32_e32 v14, 1, v12
	global_store_dwordx2 v[10:11], v[8:9], off offset:1024
	v_lshl_or_b32 v8, v14, 10, v22
	ds_read_b128 v[8:11], v8 offset:23552
	v_or_b32_e32 v12, 2, v12
	s_waitcnt lgkmcnt(0)
	v_add_f32_e32 v13, v8, v9
	v_add_f32_e32 v13, v13, v10
	v_add_f32_e32 v13, v13, v11
	ds_bpermute_b32 v15, v21, v13
	s_waitcnt lgkmcnt(0)
	v_add_f32_e32 v13, v13, v15
	ds_bpermute_b32 v15, v20, v13
	s_waitcnt lgkmcnt(0)
	v_add_f32_e32 v13, v13, v15
	ds_bpermute_b32 v15, v19, v13
	s_waitcnt lgkmcnt(0)
	v_add_f32_e32 v13, v13, v15
	ds_bpermute_b32 v15, v18, v13
	s_waitcnt lgkmcnt(0)
	v_add_f32_e32 v13, v13, v15
	ds_bpermute_b32 v15, v17, v13
	s_waitcnt lgkmcnt(0)
	v_add_f32_e32 v13, v13, v15
	ds_bpermute_b32 v15, v16, v13
	s_waitcnt lgkmcnt(0)
	v_add_f32_e32 v13, v13, v15
	v_mul_f32_e32 v24, 0x3b800000, v13
	v_pk_add_f32 v[8:9], v[8:9], v[24:25] op_sel_hi:[1,0] neg_lo:[0,1] neg_hi:[0,1]
	v_pk_add_f32 v[10:11], v[10:11], v[24:25] op_sel_hi:[1,0] neg_lo:[0,1] neg_hi:[0,1]
	v_pk_mul_f32 v[24:25], v[8:9], v[8:9]
	v_pk_mul_f32 v[26:27], v[10:11], v[10:11]
	v_add_f32_e32 v13, v24, v25
	v_add_f32_e32 v13, v26, v13
	v_add_f32_e32 v13, v27, v13
	ds_bpermute_b32 v15, v21, v13
	s_waitcnt lgkmcnt(0)
	v_add_f32_e32 v13, v13, v15
	ds_bpermute_b32 v15, v20, v13
	s_waitcnt lgkmcnt(0)
	v_add_f32_e32 v13, v13, v15
	ds_bpermute_b32 v15, v19, v13
	s_waitcnt lgkmcnt(0)
	v_add_f32_e32 v13, v13, v15
	ds_bpermute_b32 v15, v18, v13
	s_waitcnt lgkmcnt(0)
	v_add_f32_e32 v13, v13, v15
	ds_bpermute_b32 v15, v17, v13
	s_waitcnt lgkmcnt(0)
	v_add_f32_e32 v13, v13, v15
	ds_bpermute_b32 v15, v16, v13
	s_waitcnt lgkmcnt(0)
	v_add_f32_e32 v13, v13, v15
	v_fmamk_f32 v13, v13, 0x3b800000, v28
	v_cmp_gt_f32_e32 vcc, s1, v13
	v_mul_f32_e32 v15, 0x4b800000, v13
	s_nop 0
	v_cndmask_b32_e32 v13, v13, v15, vcc
	v_rsq_f32_e32 v13, v13
	s_nop 0
	v_mul_f32_e32 v15, 0x45800000, v13
	v_cndmask_b32_e32 v13, v13, v15, vcc
	v_mul_f32_e32 v8, v8, v13
	v_fma_f32 v8, v4, v8, v0
	v_mul_f32_e32 v9, v9, v13
	v_mul_f32_e32 v10, v10, v13
	v_mul_f32_e32 v11, v11, v13
	v_mul_f32_e32 v13, 0xbfb8aa3b, v8
	v_exp_f32_e32 v13, v13
	v_fma_f32 v9, v5, v9, v1
	v_fma_f32 v10, v6, v10, v2
	v_fma_f32 v11, v7, v11, v3
	v_add_f32_e32 v13, 1.0, v13
	v_div_scale_f32 v15, s[12:13], v13, v13, 1.0
	v_rcp_f32_e32 v24, v15
	s_nop 0
	v_fma_f32 v25, -v15, v24, 1.0
	v_fmac_f32_e32 v24, v25, v24
	v_div_scale_f32 v25, vcc, 1.0, v13, 1.0
	v_mul_f32_e32 v26, v25, v24
	v_fma_f32 v27, -v15, v26, v25
	v_fmac_f32_e32 v26, v27, v24
	v_fma_f32 v15, -v15, v26, v25
	v_div_fmas_f32 v15, v15, v24, v26
	v_div_fixup_f32 v13, v15, v13, 1.0
	v_mul_f32_e32 v8, v8, v13
	v_mul_f32_e32 v13, 0xbfb8aa3b, v9
	v_exp_f32_e32 v13, v13
	s_nop 0
	v_add_f32_e32 v13, 1.0, v13
	v_div_scale_f32 v15, s[12:13], v13, v13, 1.0
	v_rcp_f32_e32 v24, v15
	s_nop 0
	v_fma_f32 v25, -v15, v24, 1.0
	v_fmac_f32_e32 v24, v25, v24
	v_div_scale_f32 v25, vcc, 1.0, v13, 1.0
	v_mul_f32_e32 v26, v25, v24
	v_fma_f32 v27, -v15, v26, v25
	v_fmac_f32_e32 v26, v27, v24
	v_fma_f32 v15, -v15, v26, v25
	v_div_fmas_f32 v15, v15, v24, v26
	v_div_fixup_f32 v13, v15, v13, 1.0
	v_mul_f32_e32 v9, v9, v13
	v_mul_f32_e32 v13, 0xbfb8aa3b, v10
	v_exp_f32_e32 v13, v13
	v_cvt_pk_bf16_f32 v8, v8, v9
	s_nop 0
	v_add_f32_e32 v13, 1.0, v13
	v_div_scale_f32 v15, s[12:13], v13, v13, 1.0
	v_rcp_f32_e32 v24, v15
	s_nop 0
	v_fma_f32 v25, -v15, v24, 1.0
	v_fmac_f32_e32 v24, v25, v24
	v_div_scale_f32 v25, vcc, 1.0, v13, 1.0
	v_mul_f32_e32 v26, v25, v24
	v_fma_f32 v27, -v15, v26, v25
	v_fmac_f32_e32 v26, v27, v24
	v_fma_f32 v15, -v15, v26, v25
	v_div_fmas_f32 v15, v15, v24, v26
	v_div_fixup_f32 v13, v15, v13, 1.0
	v_mul_f32_e32 v10, v10, v13
	v_mul_f32_e32 v13, 0xbfb8aa3b, v11
	v_exp_f32_e32 v13, v13
	s_nop 0
	v_add_f32_e32 v13, 1.0, v13
	v_div_scale_f32 v15, s[12:13], v13, v13, 1.0
	v_rcp_f32_e32 v24, v15
	s_nop 0
	v_fma_f32 v25, -v15, v24, 1.0
	v_fmac_f32_e32 v24, v25, v24
	v_div_scale_f32 v25, vcc, 1.0, v13, 1.0
	v_mul_f32_e32 v26, v25, v24
	v_fma_f32 v27, -v15, v26, v25
	v_fmac_f32_e32 v26, v27, v24
	v_fma_f32 v15, -v15, v26, v25
	v_div_fmas_f32 v15, v15, v24, v26
	v_div_fixup_f32 v13, v15, v13, 1.0
	v_mul_f32_e32 v11, v11, v13
	v_ashrrev_i32_e32 v15, 31, v14
	v_cvt_pk_bf16_f32 v9, v10, v11
	v_lshl_add_u64 v[10:11], s[34:35], 0, v[14:15]
	v_lshlrev_b64 v[10:11], 11, v[10:11]
	v_lshl_add_u64 v[10:11], s[14:15], 0, v[10:11]
	v_lshl_add_u64 v[10:11], v[10:11], 0, v[112:113]
	global_store_dwordx2 v[10:11], v[8:9], off offset:1024
	v_lshl_or_b32 v8, v12, 10, v22
	ds_read_b128 v[8:11], v8 offset:23552
	s_waitcnt lgkmcnt(0)
; __device__ __forceinline__ unsigned pk_bf16(float lo, float hi) { unsigned r; asm("v_cvt_pk_bf16_f32 %0, %1, %2" : "=v"(r) : "v"(lo), "v"(hi)); return r; }
; __device__ __forceinline__ float sigmoidf_(float x) { return 1.0f / (1.0f + __expf(-x)); }
; __device__ void conv_item(const Params& p, int l, int item, char* smem) {
;     ...
;         const float4 y = *(const float4*)(sY + tl * 256 + lane * 4);
;         const float s1 = wave_sum(y.x + y.y + y.z + y.w);
;         const float mean = s1 * (1.0f / 256.0f);
;         const float dx = y.x - mean, dy = y.y - mean, dz = y.z - mean, dw = y.w - mean;
;         const float s2 = wave_sum(dx * dx + dy * dy + dz * dz + dw * dw);
;         const float rstd = rsqrtf(s2 * (1.0f / 256.0f) + EPS);
;         float o0 = dx * rstd * g4.x + b4.x, o1 = dy * rstd * g4.y + b4.y, o2 = dz * rstd * g4.z + b4.z, o3 = dw * rstd * g4.w + b4.w;
;         o0 *= sigmoidf_(o0); o1 *= sigmoidf_(o1); o2 *= sigmoidf_(o2); o3 *= sigmoidf_(o3);
;         uint2 w; w.x = pk_bf16(o0, o1); w.y = pk_bf16(o2, o3);
;         *(uint2*)(p.mixed + ((size_t)b * S + t0 + tl) * 1024 + 512 + lane * 4) = w;
	v_add_f32_e32 v13, v8, v9
	v_add_f32_e32 v13, v13, v10
	v_add_f32_e32 v13, v13, v11
	ds_bpermute_b32 v14, v21, v13
	s_waitcnt lgkmcnt(0)
	v_add_f32_e32 v13, v13, v14
	ds_bpermute_b32 v14, v20, v13
	s_waitcnt lgkmcnt(0)
	v_add_f32_e32 v13, v13, v14
	ds_bpermute_b32 v14, v19, v13
	s_waitcnt lgkmcnt(0)
	v_add_f32_e32 v13, v13, v14
	ds_bpermute_b32 v14, v18, v13
	s_waitcnt lgkmcnt(0)
	v_add_f32_e32 v13, v13, v14
	ds_bpermute_b32 v14, v17, v13
	s_waitcnt lgkmcnt(0)
	v_add_f32_e32 v13, v13, v14
	ds_bpermute_b32 v14, v16, v13
	s_waitcnt lgkmcnt(0)
	v_add_f32_e32 v13, v13, v14
	v_mul_f32_e32 v14, 0x3b800000, v13
	v_pk_add_f32 v[8:9], v[8:9], v[14:15] op_sel_hi:[1,0] neg_lo:[0,1] neg_hi:[0,1]
	v_pk_add_f32 v[10:11], v[10:11], v[14:15] op_sel_hi:[1,0] neg_lo:[0,1] neg_hi:[0,1]
	v_pk_mul_f32 v[14:15], v[8:9], v[8:9]
	v_pk_mul_f32 v[24:25], v[10:11], v[10:11]
	v_add_f32_e32 v13, v14, v15
	v_add_f32_e32 v13, v24, v13
	v_add_f32_e32 v13, v25, v13
	ds_bpermute_b32 v14, v21, v13
	s_waitcnt lgkmcnt(0)
	v_add_f32_e32 v13, v13, v14
	ds_bpermute_b32 v14, v20, v13
	s_waitcnt lgkmcnt(0)
	v_add_f32_e32 v13, v13, v14
	ds_bpermute_b32 v14, v19, v13
	s_waitcnt lgkmcnt(0)
	v_add_f32_e32 v13, v13, v14
	ds_bpermute_b32 v14, v18, v13
	s_waitcnt lgkmcnt(0)
	v_add_f32_e32 v13, v13, v14
	ds_bpermute_b32 v14, v17, v13
	s_waitcnt lgkmcnt(0)
	v_add_f32_e32 v13, v13, v14
	ds_bpermute_b32 v14, v16, v13
	s_waitcnt lgkmcnt(0)
	v_add_f32_e32 v13, v13, v14
	v_fmamk_f32 v13, v13, 0x3b800000, v28
	v_cmp_gt_f32_e32 vcc, s1, v13
	v_mul_f32_e32 v14, 0x4b800000, v13
	s_nop 0
	v_cndmask_b32_e32 v13, v13, v14, vcc
	v_rsq_f32_e32 v13, v13
	s_nop 0
	v_mul_f32_e32 v14, 0x45800000, v13
	v_cndmask_b32_e32 v13, v13, v14, vcc
	v_mul_f32_e32 v8, v8, v13
	v_fma_f32 v8, v4, v8, v0
	v_mul_f32_e32 v9, v9, v13
	v_mul_f32_e32 v10, v10, v13
	v_mul_f32_e32 v11, v11, v13
	v_mul_f32_e32 v13, 0xbfb8aa3b, v8
	v_exp_f32_e32 v13, v13
	v_fma_f32 v9, v5, v9, v1
	v_fma_f32 v10, v6, v10, v2
	v_fma_f32 v11, v7, v11, v3
	v_add_f32_e32 v13, 1.0, v13
	v_div_scale_f32 v14, s[12:13], v13, v13, 1.0
	v_rcp_f32_e32 v15, v14
	s_nop 0
	v_fma_f32 v24, -v14, v15, 1.0
	v_fmac_f32_e32 v15, v24, v15
	v_div_scale_f32 v24, vcc, 1.0, v13, 1.0
	v_mul_f32_e32 v25, v24, v15
	v_fma_f32 v26, -v14, v25, v24
	v_fmac_f32_e32 v25, v26, v15
	v_fma_f32 v14, -v14, v25, v24
	v_div_fmas_f32 v14, v14, v15, v25
	v_div_fixup_f32 v13, v14, v13, 1.0
	v_mul_f32_e32 v8, v8, v13
	v_mul_f32_e32 v13, 0xbfb8aa3b, v9
	v_exp_f32_e32 v13, v13
	s_nop 0
	v_add_f32_e32 v13, 1.0, v13
	v_div_scale_f32 v14, s[12:13], v13, v13, 1.0
	v_rcp_f32_e32 v15, v14
	s_nop 0
	v_fma_f32 v24, -v14, v15, 1.0
	v_fmac_f32_e32 v15, v24, v15
	v_div_scale_f32 v24, vcc, 1.0, v13, 1.0
	v_mul_f32_e32 v25, v24, v15
	v_fma_f32 v26, -v14, v25, v24
	v_fmac_f32_e32 v25, v26, v15
	v_fma_f32 v14, -v14, v25, v24
	v_div_fmas_f32 v14, v14, v15, v25
	v_div_fixup_f32 v13, v14, v13, 1.0
	v_mul_f32_e32 v9, v9, v13
	v_mul_f32_e32 v13, 0xbfb8aa3b, v10
	v_exp_f32_e32 v13, v13
	v_cvt_pk_bf16_f32 v8, v8, v9
	s_nop 0
	v_add_f32_e32 v13, 1.0, v13
	v_div_scale_f32 v14, s[12:13], v13, v13, 1.0
	v_rcp_f32_e32 v15, v14
	s_nop 0
	v_fma_f32 v24, -v14, v15, 1.0
	v_fmac_f32_e32 v15, v24, v15
	v_div_scale_f32 v24, vcc, 1.0, v13, 1.0
	v_mul_f32_e32 v25, v24, v15
	v_fma_f32 v26, -v14, v25, v24
	v_fmac_f32_e32 v25, v26, v15
	v_fma_f32 v14, -v14, v25, v24
	v_div_fmas_f32 v14, v14, v15, v25
	v_div_fixup_f32 v13, v14, v13, 1.0
	v_mul_f32_e32 v10, v10, v13
	v_mul_f32_e32 v13, 0xbfb8aa3b, v11
	v_exp_f32_e32 v13, v13
	s_nop 0
	v_add_f32_e32 v13, 1.0, v13
	v_div_scale_f32 v14, s[12:13], v13, v13, 1.0
	v_rcp_f32_e32 v15, v14
	s_nop 0
	v_fma_f32 v24, -v14, v15, 1.0
	v_fmac_f32_e32 v15, v24, v15
	v_div_scale_f32 v24, vcc, 1.0, v13, 1.0
	v_mul_f32_e32 v25, v24, v15
	v_fma_f32 v26, -v14, v25, v24
	v_fmac_f32_e32 v25, v26, v15
	v_fma_f32 v14, -v14, v25, v24
	v_div_fmas_f32 v14, v14, v15, v25
	v_div_fixup_f32 v13, v14, v13, 1.0
	v_mul_f32_e32 v11, v11, v13
	v_ashrrev_i32_e32 v13, 31, v12
	v_cvt_pk_bf16_f32 v9, v10, v11
	v_lshl_add_u64 v[10:11], s[34:35], 0, v[12:13]
	v_lshlrev_b64 v[10:11], 11, v[10:11]
	v_lshl_add_u64 v[10:11], s[14:15], 0, v[10:11]
	v_lshl_add_u64 v[10:11], v[10:11], 0, v[112:113]
	v_or_b32_e32 v12, 3, v23
	global_store_dwordx2 v[10:11], v[8:9], off offset:1024
	v_lshl_or_b32 v8, v12, 10, v22
	ds_read_b128 v[8:11], v8 offset:23552
	s_waitcnt lgkmcnt(0)
; __device__ __forceinline__ unsigned pk_bf16(float lo, float hi) { unsigned r; asm("v_cvt_pk_bf16_f32 %0, %1, %2" : "=v"(r) : "v"(lo), "v"(hi)); return r; }
; __device__ __forceinline__ float sigmoidf_(float x) { return 1.0f / (1.0f + __expf(-x)); }
; __device__ void conv_item(const Params& p, int l, int item, char* smem) {
;     ...
;         const float4 y = *(const float4*)(sY + tl * 256 + lane * 4);
;         const float s1 = wave_sum(y.x + y.y + y.z + y.w);
;         const float mean = s1 * (1.0f / 256.0f);
;         const float dx = y.x - mean, dy = y.y - mean, dz = y.z - mean, dw = y.w - mean;
;         const float s2 = wave_sum(dx * dx + dy * dy + dz * dz + dw * dw);
;         const float rstd = rsqrtf(s2 * (1.0f / 256.0f) + EPS);
;         float o0 = dx * rstd * g4.x + b4.x, o1 = dy * rstd * g4.y + b4.y, o2 = dz * rstd * g4.z + b4.z, o3 = dw * rstd * g4.w + b4.w;
;         o0 *= sigmoidf_(o0); o1 *= sigmoidf_(o1); o2 *= sigmoidf_(o2); o3 *= sigmoidf_(o3);
;         uint2 w; w.x = pk_bf16(o0, o1); w.y = pk_bf16(o2, o3);
;         *(uint2*)(p.mixed + ((size_t)b * S + t0 + tl) * 1024 + 512 + lane * 4) = w;
;     }
;     __syncthreads();
	v_add_f32_e32 v13, v8, v9
	v_add_f32_e32 v13, v13, v10
	v_add_f32_e32 v13, v13, v11
	ds_bpermute_b32 v14, v21, v13
	s_waitcnt lgkmcnt(0)
	v_add_f32_e32 v13, v13, v14
	ds_bpermute_b32 v14, v20, v13
	s_waitcnt lgkmcnt(0)
	v_add_f32_e32 v13, v13, v14
	ds_bpermute_b32 v14, v19, v13
	s_waitcnt lgkmcnt(0)
	v_add_f32_e32 v13, v13, v14
	ds_bpermute_b32 v14, v18, v13
	s_waitcnt lgkmcnt(0)
	v_add_f32_e32 v13, v13, v14
	ds_bpermute_b32 v14, v17, v13
	s_waitcnt lgkmcnt(0)
	v_add_f32_e32 v13, v13, v14
	ds_bpermute_b32 v14, v16, v13
	s_waitcnt lgkmcnt(0)
	v_add_f32_e32 v13, v13, v14
	v_mul_f32_e32 v14, 0x3b800000, v13
	v_pk_add_f32 v[8:9], v[8:9], v[14:15] op_sel_hi:[1,0] neg_lo:[0,1] neg_hi:[0,1]
	v_pk_add_f32 v[10:11], v[10:11], v[14:15] op_sel_hi:[1,0] neg_lo:[0,1] neg_hi:[0,1]
	v_pk_mul_f32 v[14:15], v[8:9], v[8:9]
	v_pk_mul_f32 v[22:23], v[10:11], v[10:11]
	v_add_f32_e32 v13, v14, v15
	v_add_f32_e32 v13, v22, v13
	v_add_f32_e32 v13, v23, v13
	ds_bpermute_b32 v14, v21, v13
	s_waitcnt lgkmcnt(0)
	v_add_f32_e32 v13, v13, v14
	ds_bpermute_b32 v14, v20, v13
	s_waitcnt lgkmcnt(0)
	v_add_f32_e32 v13, v13, v14
	ds_bpermute_b32 v14, v19, v13
	s_waitcnt lgkmcnt(0)
	v_add_f32_e32 v13, v13, v14
	ds_bpermute_b32 v14, v18, v13
	s_waitcnt lgkmcnt(0)
	v_add_f32_e32 v13, v13, v14
	ds_bpermute_b32 v14, v17, v13
	s_waitcnt lgkmcnt(0)
	v_add_f32_e32 v13, v13, v14
	ds_bpermute_b32 v14, v16, v13
	s_waitcnt lgkmcnt(0)
	v_add_f32_e32 v13, v13, v14
	v_fmamk_f32 v13, v13, 0x3b800000, v28
	v_cmp_gt_f32_e32 vcc, s1, v13
	v_mul_f32_e32 v14, 0x4b800000, v13
	s_nop 0
	v_cndmask_b32_e32 v13, v13, v14, vcc
	v_rsq_f32_e32 v13, v13
	s_nop 0
	v_mul_f32_e32 v14, 0x45800000, v13
	v_cndmask_b32_e32 v13, v13, v14, vcc
	v_mul_f32_e32 v8, v8, v13
	v_fma_f32 v0, v4, v8, v0
	v_mul_f32_e32 v4, v9, v13
	v_fma_f32 v1, v5, v4, v1
	v_mul_f32_e32 v4, v10, v13
	v_fma_f32 v2, v6, v4, v2
	v_mul_f32_e32 v4, v11, v13
	v_fmac_f32_e32 v3, v7, v4
	v_mul_f32_e32 v4, 0xbfb8aa3b, v0
	v_exp_f32_e32 v4, v4
	v_ashrrev_i32_e32 v13, 31, v12
	v_add_f32_e32 v4, 1.0, v4
	v_div_scale_f32 v5, s[12:13], v4, v4, 1.0
	v_rcp_f32_e32 v6, v5
	s_nop 0
	v_fma_f32 v7, -v5, v6, 1.0
	v_fmac_f32_e32 v6, v7, v6
	v_div_scale_f32 v7, vcc, 1.0, v4, 1.0
	v_mul_f32_e32 v8, v7, v6
	v_fma_f32 v9, -v5, v8, v7
	v_fmac_f32_e32 v8, v9, v6
	v_fma_f32 v5, -v5, v8, v7
	v_div_fmas_f32 v5, v5, v6, v8
	v_div_fixup_f32 v4, v5, v4, 1.0
	v_mul_f32_e32 v0, v0, v4
	v_mul_f32_e32 v4, 0xbfb8aa3b, v1
	v_exp_f32_e32 v4, v4
	s_nop 0
	v_add_f32_e32 v4, 1.0, v4
	v_div_scale_f32 v5, s[12:13], v4, v4, 1.0
	v_rcp_f32_e32 v6, v5
	s_nop 0
	v_fma_f32 v7, -v5, v6, 1.0
	v_fmac_f32_e32 v6, v7, v6
	v_div_scale_f32 v7, vcc, 1.0, v4, 1.0
	v_mul_f32_e32 v8, v7, v6
	v_fma_f32 v9, -v5, v8, v7
	v_fmac_f32_e32 v8, v9, v6
	v_fma_f32 v5, -v5, v8, v7
	v_div_fmas_f32 v5, v5, v6, v8
	v_div_fixup_f32 v4, v5, v4, 1.0
	v_mul_f32_e32 v1, v1, v4
	v_mul_f32_e32 v4, 0xbfb8aa3b, v2
	v_exp_f32_e32 v4, v4
	v_cvt_pk_bf16_f32 v0, v0, v1
	s_nop 0
	v_add_f32_e32 v4, 1.0, v4
	v_div_scale_f32 v5, s[12:13], v4, v4, 1.0
	v_rcp_f32_e32 v6, v5
	s_nop 0
	v_fma_f32 v7, -v5, v6, 1.0
	v_fmac_f32_e32 v6, v7, v6
	v_div_scale_f32 v7, vcc, 1.0, v4, 1.0
	v_mul_f32_e32 v8, v7, v6
	v_fma_f32 v9, -v5, v8, v7
	v_fmac_f32_e32 v8, v9, v6
	v_fma_f32 v5, -v5, v8, v7
	v_div_fmas_f32 v5, v5, v6, v8
	v_div_fixup_f32 v4, v5, v4, 1.0
	v_mul_f32_e32 v2, v2, v4
	v_mul_f32_e32 v4, 0xbfb8aa3b, v3
	v_exp_f32_e32 v4, v4
	s_nop 0
	v_add_f32_e32 v4, 1.0, v4
	v_div_scale_f32 v5, s[12:13], v4, v4, 1.0
	v_rcp_f32_e32 v6, v5
	s_nop 0
	v_fma_f32 v7, -v5, v6, 1.0
	v_fmac_f32_e32 v6, v7, v6
	v_div_scale_f32 v7, vcc, 1.0, v4, 1.0
	v_mul_f32_e32 v8, v7, v6
	v_fma_f32 v9, -v5, v8, v7
	v_fmac_f32_e32 v8, v9, v6
	v_fma_f32 v5, -v5, v8, v7
	v_div_fmas_f32 v5, v5, v6, v8
	v_div_fixup_f32 v4, v5, v4, 1.0
	v_mul_f32_e32 v3, v3, v4
	v_cvt_pk_bf16_f32 v1, v2, v3
	v_lshl_add_u64 v[2:3], s[34:35], 0, v[12:13]
	v_lshlrev_b64 v[2:3], 11, v[2:3]
	v_lshl_add_u64 v[2:3], s[14:15], 0, v[2:3]
	v_lshl_add_u64 v[2:3], v[2:3], 0, v[112:113]
	global_store_dwordx2 v[2:3], v[0:1], off offset:1024
	s_barrier
	s_cbranch_scc0 .LBB0_160

; __device__ void rnn1_item(const Params& p, int l, int item, char* smem) {
;     ...
;         const float* wr = p.rg_w_r + ((size_t)l * 4 + hb) * 4096; const float* wi = p.rg_w_i + ((size_t)l * 4 + hb) * 4096;
; #pragma unroll
;         for (int i = 0; i < 16; ++i) { sWr[tid + 256 * i] = wr[tid + 256 * i]; sWi[tid + 256 * i] = wi[tid + 256 * i]; }
;     }
;     const int ch = hb * 64 + c;
;     float cw[4];
; #pragma unroll
;     for (int k = 0; k < 4; ++k) cw[k] = p.rg_conv_w[((size_t)l * 4 + k) * 256 + ch];
;     const float cb = p.rg_conv_b[l * 256 + ch];
;     __syncthreads();
.LBB0_209:
	s_or_b64 exec, exec, s[22:23]
	s_lshl_b32 s0, s16, 12
	s_or_b32 s0, s34, s0
	s_mov_b32 s1, s35
	v_readlane_b32 s68, v165, 10
	s_lshl_b64 s[0:1], s[0:1], 2
	v_readlane_b32 s72, v165, 14
	v_readlane_b32 s73, v165, 15
	s_add_u32 s16, s72, s0
	v_readlane_b32 s76, v165, 18
	s_addc_u32 s17, s73, s1
	v_readlane_b32 s77, v165, 19
	s_add_u32 s0, s76, s0
	v_ashrrev_i32_e32 v5, 31, v4
	s_addc_u32 s1, s77, s1
	v_lshlrev_b64 v[0:1], 2, v[4:5]
	v_lshl_add_u64 v[2:3], s[16:17], 0, v[0:1]
	v_lshl_add_u64 v[0:1], s[0:1], 0, v[0:1]
	s_movk_i32 s0, 0x1000
	v_add_co_u32_e32 v6, vcc, s0, v2
	s_movk_i32 s1, 0x2000
	s_nop 0
	v_addc_co_u32_e32 v7, vcc, 0, v3, vcc
	v_add_co_u32_e32 v8, vcc, s1, v2
	global_load_dword v14, v[2:3], off
	global_load_dword v15, v[2:3], off offset:1024
	global_load_dword v16, v[2:3], off offset:2048
	global_load_dword v17, v[2:3], off offset:3072
	global_load_dword v18, v[0:1], off
	global_load_dword v19, v[0:1], off offset:1024
	global_load_dword v20, v[0:1], off offset:2048
	global_load_dword v21, v[0:1], off offset:3072
	v_addc_co_u32_e32 v9, vcc, 0, v3, vcc
	v_add_co_u32_e32 v10, vcc, s0, v0
	s_movk_i32 s0, 0x3000
	s_nop 0
	v_addc_co_u32_e32 v11, vcc, 0, v1, vcc
	v_add_co_u32_e32 v12, vcc, s1, v0
	v_and_b32_e32 v5, 63, v4
	s_nop 0
	v_addc_co_u32_e32 v13, vcc, 0, v1, vcc
	v_add_co_u32_e32 v2, vcc, s0, v2
	global_load_dword v22, v[6:7], off offset:1024
	global_load_dword v23, v[6:7], off offset:2048
	s_nop 0
	global_load_dword v6, v[6:7], off offset:3072
	s_nop 0
	global_load_dword v7, v[10:11], off offset:1024
	global_load_dword v24, v[10:11], off offset:2048
	s_nop 0
	global_load_dword v10, v[10:11], off offset:3072
	s_nop 0
	global_load_dword v11, v[8:9], off offset:-4096
	global_load_dword v25, v[8:9], off
	global_load_dword v26, v[8:9], off offset:1024
	global_load_dword v27, v[8:9], off offset:2048
	s_nop 0
	global_load_dword v8, v[8:9], off offset:3072
	s_nop 0
	global_load_dword v9, v[12:13], off offset:-4096
	global_load_dword v28, v[12:13], off
	global_load_dword v29, v[12:13], off offset:1024
	global_load_dword v30, v[12:13], off offset:2048
	s_nop 0
	global_load_dword v12, v[12:13], off offset:3072
	v_addc_co_u32_e32 v3, vcc, 0, v3, vcc
	v_add_co_u32_e32 v0, vcc, s0, v0
	v_readlane_b32 s70, v165, 12
	s_nop 0
	v_addc_co_u32_e32 v1, vcc, 0, v1, vcc
	global_load_dword v13, v[2:3], off
	global_load_dword v31, v[2:3], off offset:1024
	global_load_dword v32, v[2:3], off offset:2048
	global_load_dword v33, v[2:3], off offset:3072
	global_load_dword v36, v[0:1], off
	global_load_dword v37, v[0:1], off offset:1024
	global_load_dword v38, v[0:1], off offset:2048
	global_load_dword v41, v[0:1], off offset:3072
	v_or_b32_e32 v0, s14, v5
	v_or_b32_e32 v34, s12, v0
	v_readlane_b32 s71, v165, 13
	v_ashrrev_i32_e32 v35, 31, v34
	v_lshlrev_b32_e32 v1, 2, v0
	v_lshl_add_u64 v[2:3], v[34:35], 2, s[70:71]
	global_load_dword v39, v[2:3], off
	global_load_dword v57, v1, s[38:39]
	global_load_dword v58, v1, s[38:39] offset:1024
	global_load_dword v59, v1, s[38:39] offset:2048
	global_load_dword v60, v1, s[38:39] offset:3072
	v_ashrrev_i32_e32 v1, 6, v4
	v_lshlrev_b32_e32 v40, 2, v4
	s_mov_b32 s0, 0
	v_readlane_b32 s69, v165, 11
	v_readlane_b32 s74, v165, 16
	v_readlane_b32 s75, v165, 17
	v_readlane_b32 s78, v165, 20
	v_readlane_b32 s79, v165, 21
	v_readlane_b32 s80, v165, 22
	v_readlane_b32 s81, v165, 23
	v_readlane_b32 s82, v165, 24
	v_readlane_b32 s83, v165, 25
	s_waitcnt vmcnt(35)
	ds_write2st64_b32 v40, v14, v15 offset0:67 offset1:71
	s_waitcnt vmcnt(33)
	ds_write2st64_b32 v40, v16, v17 offset0:75 offset1:79
	s_waitcnt vmcnt(22)
	ds_write2st64_b32 v40, v11, v22 offset0:83 offset1:87
	ds_write2st64_b32 v40, v23, v6 offset0:91 offset1:95
	s_waitcnt vmcnt(20)
	ds_write2st64_b32 v40, v25, v26 offset0:99 offset1:103
	ds_write2st64_b32 v40, v18, v19 offset0:131 offset1:135
	ds_write2st64_b32 v40, v20, v21 offset0:139 offset1:143
	s_waitcnt vmcnt(17)
	ds_write2st64_b32 v40, v9, v7 offset0:147 offset1:151
	ds_write2st64_b32 v40, v24, v10 offset0:155 offset1:159
	s_waitcnt vmcnt(15)
	ds_write2st64_b32 v40, v28, v29 offset0:163 offset1:167
	ds_write2st64_b32 v40, v27, v8 offset0:107 offset1:111
	s_waitcnt vmcnt(13)
	ds_write2st64_b32 v40, v30, v12 offset0:171 offset1:175
	s_waitcnt vmcnt(11)
	ds_write2st64_b32 v40, v13, v31 offset0:115 offset1:119
	s_waitcnt vmcnt(7)
	ds_write2st64_b32 v40, v36, v37 offset0:179 offset1:183
	ds_write2st64_b32 v40, v32, v33 offset0:123 offset1:127
	s_waitcnt vmcnt(5)
	ds_write2st64_b32 v40, v38, v41 offset0:187 offset1:191
	v_lshlrev_b32_e32 v41, 2, v5
	v_lshlrev_b32_e32 v38, 12, v1
	v_or_b32_e32 v14, v38, v41
	s_waitcnt lgkmcnt(0)
	s_barrier
; __device__ void rnn1_item(const Params& p, int l, int item, char* smem) {
;     ...
;     float xc[16];
; #pragma unroll
;     for (int i = 0; i < 16; ++i) {
;         const int tl = q * 16 + i;
;         xc[i] = cb + cw[0] * sX[(tl + 0) * 64 + c] + cw[1] * sX[(tl + 1) * 64 + c] + cw[2] * sX[(tl + 2) * 64 + c] + cw[3] * sX[(tl + 3) * 64 + c];
;     }
;     __syncthreads();
; #pragma unroll
;     for (int i = 0; i < 16; ++i) sX[(q * 16 + i) * 64 + c] = xc[i];
;     __syncthreads();
;     float ar[16], ai[16];
; #pragma unroll
;     for (int i = 0; i < 16; ++i) { ar[i] = 0.f; ai[i] = 0.f; }
;     for (int k = 0; k < 64; ++k) {
;         const float wrv = sWr[k * 64 + c], wiv = sWi[k * 64 + c];
; #pragma unroll
;         for (int i = 0; i < 16; ++i) { const float xv = sX[(q * 16 + i) * 64 + k]; ar[i] += xv * wrv; ai[i] += xv * wiv; }
;     }
	ds_read2st64_b32 v[2:3], v14 offset1:1
	ds_read2st64_b32 v[6:7], v14 offset0:2 offset1:3
	ds_read2st64_b32 v[8:9], v14 offset0:4 offset1:5
	ds_read2st64_b32 v[10:11], v14 offset0:6 offset1:7
	v_mov_b32_e32 v18, 0
	v_mov_b32_e32 v19, v18
	s_waitcnt vmcnt(3) lgkmcnt(2)
	v_fma_f32 v54, v57, v6, v39
	v_fma_f32 v56, v57, v2, v39
	s_waitcnt vmcnt(2)
	v_fmac_f32_e32 v56, v58, v3
	v_fma_f32 v55, v57, v3, v39
	ds_read2st64_b32 v[2:3], v14 offset0:8 offset1:9
	v_fmac_f32_e32 v55, v58, v6
	v_fmac_f32_e32 v54, v58, v7
	v_fma_f32 v53, v57, v7, v39
	s_waitcnt lgkmcnt(2)
	v_fma_f32 v51, v57, v9, v39
	s_waitcnt lgkmcnt(1)
	v_fma_f32 v50, v57, v10, v39
	s_waitcnt vmcnt(1)
	v_fmac_f32_e32 v56, v59, v6
	v_fmac_f32_e32 v55, v59, v7
	v_fmac_f32_e32 v54, v59, v8
	v_fmac_f32_e32 v53, v58, v8
	v_fma_f32 v52, v57, v8, v39
	v_fmac_f32_e32 v51, v58, v10
	v_fmac_f32_e32 v50, v58, v11
	v_fma_f32 v49, v57, v11, v39
	s_waitcnt vmcnt(0)
	v_fmac_f32_e32 v56, v60, v7
	v_fmac_f32_e32 v55, v60, v8
	v_fmac_f32_e32 v54, v60, v9
	v_fmac_f32_e32 v53, v59, v9
	v_fmac_f32_e32 v52, v58, v9
	v_fmac_f32_e32 v51, v59, v11
	ds_read2st64_b32 v[6:7], v14 offset0:10 offset1:11
	ds_read2st64_b32 v[8:9], v14 offset0:12 offset1:13
	ds_read2st64_b32 v[12:13], v14 offset0:14 offset1:15
	s_waitcnt lgkmcnt(3)
	v_fmac_f32_e32 v50, v59, v2
	v_fmac_f32_e32 v49, v58, v2
	v_fma_f32 v48, v57, v2, v39
	v_fmac_f32_e32 v51, v60, v2
	v_fmac_f32_e32 v50, v60, v3
	v_fmac_f32_e32 v49, v59, v3
	v_fmac_f32_e32 v48, v58, v3
	v_fma_f32 v47, v57, v3, v39
	ds_read2st64_b32 v[2:3], v14 offset0:16 offset1:17
	s_waitcnt lgkmcnt(3)
	v_fmac_f32_e32 v49, v60, v6
	v_fmac_f32_e32 v48, v59, v6
	v_fmac_f32_e32 v47, v58, v6
	v_fma_f32 v46, v57, v6, v39
	ds_read_b32 v6, v14 offset:4608
	v_fma_f32 v45, v57, v7, v39
	s_waitcnt lgkmcnt(3)
	v_fma_f32 v44, v57, v8, v39
	v_fma_f32 v43, v57, v9, v39
	s_waitcnt lgkmcnt(2)
	v_fma_f32 v42, v57, v12, v39
	v_fmac_f32_e32 v39, v57, v13
	v_fmac_f32_e32 v46, v58, v7
	v_fmac_f32_e32 v45, v58, v8
	v_fmac_f32_e32 v44, v58, v9
	v_fmac_f32_e32 v43, v58, v12
	v_fmac_f32_e32 v42, v58, v13
	s_waitcnt lgkmcnt(1)
	v_fmac_f32_e32 v39, v58, v2
	v_fmac_f32_e32 v52, v59, v10
	v_fmac_f32_e32 v47, v59, v7
	v_fmac_f32_e32 v46, v59, v8
	v_fmac_f32_e32 v45, v59, v9
	v_fmac_f32_e32 v44, v59, v12
	v_fmac_f32_e32 v43, v59, v13
	v_fmac_f32_e32 v42, v59, v2
	v_fmac_f32_e32 v39, v59, v3
	v_fmac_f32_e32 v53, v60, v10
	v_fmac_f32_e32 v52, v60, v11
	v_fmac_f32_e32 v48, v60, v7
	v_fmac_f32_e32 v47, v60, v8
	v_fmac_f32_e32 v46, v60, v9
	v_fmac_f32_e32 v45, v60, v12
	v_fmac_f32_e32 v44, v60, v13
	v_fmac_f32_e32 v43, v60, v2
	v_fmac_f32_e32 v42, v60, v3
	s_waitcnt lgkmcnt(0)
	v_fmac_f32_e32 v39, v60, v6
	s_barrier
	ds_write2st64_b32 v14, v56, v55 offset1:1
	ds_write2st64_b32 v14, v54, v53 offset0:2 offset1:3
	ds_write2st64_b32 v14, v52, v51 offset0:4 offset1:5
	ds_write2st64_b32 v14, v50, v49 offset0:6 offset1:7
	ds_write2st64_b32 v14, v48, v47 offset0:8 offset1:9
	ds_write2st64_b32 v14, v46, v45 offset0:10 offset1:11
	ds_write2st64_b32 v14, v44, v43 offset0:12 offset1:13
	ds_write2st64_b32 v14, v42, v39 offset0:14 offset1:15
	v_or_b32_e32 v57, 0x4300, v41
	v_mov_b32_e32 v16, v18
	v_mov_b32_e32 v17, v18
	v_mov_b32_e32 v14, v18
	v_mov_b32_e32 v15, v18
	v_mov_b32_e32 v12, v18
	v_mov_b32_e32 v13, v18
	v_mov_b32_e32 v10, v18
	v_mov_b32_e32 v11, v18
	v_mov_b32_e32 v8, v18
	v_mov_b32_e32 v9, v18
	v_mov_b32_e32 v6, v18
	v_mov_b32_e32 v7, v18
	v_mov_b32_e32 v2, v18
	v_mov_b32_e32 v3, v18
	v_mov_b32_e32 v36, v18
	v_mov_b32_e32 v37, v18
	v_mov_b32_e32 v32, v18
	v_mov_b32_e32 v33, v18
	v_mov_b32_e32 v30, v18
	v_mov_b32_e32 v31, v18
	v_mov_b32_e32 v28, v18
	v_mov_b32_e32 v29, v18
	v_mov_b32_e32 v26, v18
	v_mov_b32_e32 v27, v18
	v_mov_b32_e32 v24, v18
	v_mov_b32_e32 v25, v18
	v_mov_b32_e32 v22, v18
	v_mov_b32_e32 v23, v18
	v_mov_b32_e32 v20, v18
	v_mov_b32_e32 v21, v18
	s_waitcnt lgkmcnt(0)
	s_barrier
	ds_read2st64_b32 v[90:91], v57 offset1:1
	ds_read2st64_b32 v[92:93], v57 offset0:64 offset1:65
	v_add_u32_e32 v154, s0, v38
	v_add_u32_e32 v155, 0x800, v154
	ds_read2_b64 v[58:61], v154 offset1:32
	ds_read2_b64 v[62:65], v154 offset0:64 offset1:96
	ds_read2_b64 v[66:69], v154 offset0:128 offset1:160
	ds_read2_b64 v[70:73], v154 offset0:192 offset1:224
	ds_read2_b64 v[74:77], v155 offset1:32
	ds_read2_b64 v[78:81], v155 offset0:64 offset1:96
	ds_read2_b64 v[82:85], v155 offset0:128 offset1:160
	ds_read2_b64 v[86:89], v155 offset0:192 offset1:224
	s_add_i32 s0, s0, 8
	v_add_u32_e32 v57, 0x200, v57
; __device__ __forceinline__ float log1p_pos(float x) { return x < 0.0625f ? x * (1.0f - x * (0.5f - x * (0.33333334f - x * (0.25f - x * 0.2f)))) : __logf(1.0f + x); }
; __device__ void rnn1_item(const Params& p, int l, int item, char* smem) {
;     ...
;     for (int k = 0; k < 64; ++k) {
;         const float wrv = sWr[k * 64 + c], wiv = sWi[k * 64 + c];
; #pragma unroll
;         for (int i = 0; i < 16; ++i) { const float xv = sX[(q * 16 + i) * 64 + k]; ar[i] += xv * wrv; ai[i] += xv * wiv; }
;     }
;     const float br = p.rg_b_r[l * 256 + ch], bi = p.rg_b_i[l * 256 + ch];
;     const float lam = p.rg_lambda[l * 256 + ch];
;     const float sp = log1p_pos(__expf(-lam));
.LBB0_210:
	s_waitcnt lgkmcnt(0)
	ds_read2st64_b32 v[94:95], v57 offset1:1
	ds_read2st64_b32 v[96:97], v57 offset0:64 offset1:65
	v_add_u32_e32 v154, s0, v38
	v_add_u32_e32 v155, 0x800, v154
	ds_read2_b64 v[98:101], v154 offset1:32
	ds_read2_b64 v[102:105], v154 offset0:64 offset1:96
	ds_read2_b64 v[106:109], v154 offset0:128 offset1:160
	ds_read2_b64 v[116:119], v154 offset0:192 offset1:224
	ds_read2_b64 v[120:123], v155 offset1:32
	ds_read2_b64 v[142:145], v155 offset0:64 offset1:96
	ds_read2_b64 v[146:149], v155 offset0:128 offset1:160
	ds_read2_b64 v[150:153], v155 offset0:192 offset1:224
	s_add_i32 s0, s0, 8
	v_add_u32_e32 v57, 0x200, v57
	v_fmac_f32_e32 v36, v90, v58
	v_fmac_f32_e32 v37, v90, v60
	v_fmac_f32_e32 v18, v92, v58
	v_fmac_f32_e32 v19, v92, v60
	v_fmac_f32_e32 v32, v90, v62
	v_fmac_f32_e32 v33, v90, v64
	v_fmac_f32_e32 v16, v92, v62
	v_fmac_f32_e32 v17, v92, v64
	v_fmac_f32_e32 v30, v90, v66
	v_fmac_f32_e32 v31, v90, v68
	v_fmac_f32_e32 v14, v92, v66
	v_fmac_f32_e32 v15, v92, v68
	v_fmac_f32_e32 v28, v90, v70
	v_fmac_f32_e32 v29, v90, v72
	v_fmac_f32_e32 v12, v92, v70
	v_fmac_f32_e32 v13, v92, v72
	v_fmac_f32_e32 v26, v90, v74
	v_fmac_f32_e32 v27, v90, v76
	v_fmac_f32_e32 v10, v92, v74
	v_fmac_f32_e32 v11, v92, v76
	v_fmac_f32_e32 v24, v90, v78
	v_fmac_f32_e32 v25, v90, v80
	v_fmac_f32_e32 v8, v92, v78
	v_fmac_f32_e32 v9, v92, v80
	v_fmac_f32_e32 v22, v90, v82
	v_fmac_f32_e32 v23, v90, v84
	v_fmac_f32_e32 v6, v92, v82
	v_fmac_f32_e32 v7, v92, v84
	v_fmac_f32_e32 v20, v90, v86
	v_fmac_f32_e32 v21, v90, v88
	v_fmac_f32_e32 v2, v92, v86
	v_fmac_f32_e32 v3, v92, v88
	v_fmac_f32_e32 v36, v91, v59
	v_fmac_f32_e32 v37, v91, v61
	v_fmac_f32_e32 v18, v93, v59
	v_fmac_f32_e32 v19, v93, v61
	v_fmac_f32_e32 v32, v91, v63
	v_fmac_f32_e32 v33, v91, v65
	v_fmac_f32_e32 v16, v93, v63
	v_fmac_f32_e32 v17, v93, v65
	v_fmac_f32_e32 v30, v91, v67
	v_fmac_f32_e32 v31, v91, v69
	v_fmac_f32_e32 v14, v93, v67
	v_fmac_f32_e32 v15, v93, v69
	v_fmac_f32_e32 v28, v91, v71
	v_fmac_f32_e32 v29, v91, v73
	v_fmac_f32_e32 v12, v93, v71
	v_fmac_f32_e32 v13, v93, v73
	v_fmac_f32_e32 v26, v91, v75
	v_fmac_f32_e32 v27, v91, v77
	v_fmac_f32_e32 v10, v93, v75
	v_fmac_f32_e32 v11, v93, v77
	v_fmac_f32_e32 v24, v91, v79
	v_fmac_f32_e32 v25, v91, v81
	v_fmac_f32_e32 v8, v93, v79
	v_fmac_f32_e32 v9, v93, v81
	v_fmac_f32_e32 v22, v91, v83
	v_fmac_f32_e32 v23, v91, v85
	v_fmac_f32_e32 v6, v93, v83
	v_fmac_f32_e32 v7, v93, v85
	v_fmac_f32_e32 v20, v91, v87
	v_fmac_f32_e32 v21, v91, v89
	v_fmac_f32_e32 v2, v93, v87
	v_fmac_f32_e32 v3, v93, v89
	s_waitcnt lgkmcnt(0)
	ds_read2st64_b32 v[90:91], v57 offset1:1
	ds_read2st64_b32 v[92:93], v57 offset0:64 offset1:65
	v_add_u32_e32 v154, s0, v38
	v_add_u32_e32 v155, 0x800, v154
	ds_read2_b64 v[58:61], v154 offset1:32
	ds_read2_b64 v[62:65], v154 offset0:64 offset1:96
	ds_read2_b64 v[66:69], v154 offset0:128 offset1:160
	ds_read2_b64 v[70:73], v154 offset0:192 offset1:224
	ds_read2_b64 v[74:77], v155 offset1:32
	ds_read2_b64 v[78:81], v155 offset0:64 offset1:96
	ds_read2_b64 v[82:85], v155 offset0:128 offset1:160
	ds_read2_b64 v[86:89], v155 offset0:192 offset1:224
	s_add_i32 s0, s0, 8
	v_add_u32_e32 v57, 0x200, v57
	v_fmac_f32_e32 v36, v94, v98
	v_fmac_f32_e32 v37, v94, v100
	v_fmac_f32_e32 v18, v96, v98
	v_fmac_f32_e32 v19, v96, v100
	v_fmac_f32_e32 v32, v94, v102
	v_fmac_f32_e32 v33, v94, v104
	v_fmac_f32_e32 v16, v96, v102
	v_fmac_f32_e32 v17, v96, v104
	v_fmac_f32_e32 v30, v94, v106
	v_fmac_f32_e32 v31, v94, v108
	v_fmac_f32_e32 v14, v96, v106
	v_fmac_f32_e32 v15, v96, v108
	v_fmac_f32_e32 v28, v94, v116
	v_fmac_f32_e32 v29, v94, v118
	v_fmac_f32_e32 v12, v96, v116
	v_fmac_f32_e32 v13, v96, v118
	v_fmac_f32_e32 v26, v94, v120
	v_fmac_f32_e32 v27, v94, v122
	v_fmac_f32_e32 v10, v96, v120
	v_fmac_f32_e32 v11, v96, v122
	v_fmac_f32_e32 v24, v94, v142
	v_fmac_f32_e32 v25, v94, v144
	v_fmac_f32_e32 v8, v96, v142
	v_fmac_f32_e32 v9, v96, v144
	v_fmac_f32_e32 v22, v94, v146
	v_fmac_f32_e32 v23, v94, v148
	v_fmac_f32_e32 v6, v96, v146
	v_fmac_f32_e32 v7, v96, v148
	v_fmac_f32_e32 v20, v94, v150
	v_fmac_f32_e32 v21, v94, v152
	v_fmac_f32_e32 v2, v96, v150
	v_fmac_f32_e32 v3, v96, v152
	v_fmac_f32_e32 v36, v95, v99
	v_fmac_f32_e32 v37, v95, v101
	v_fmac_f32_e32 v18, v97, v99
	v_fmac_f32_e32 v19, v97, v101
	v_fmac_f32_e32 v32, v95, v103
	v_fmac_f32_e32 v33, v95, v105
	v_fmac_f32_e32 v16, v97, v103
	v_fmac_f32_e32 v17, v97, v105
	v_fmac_f32_e32 v30, v95, v107
	v_fmac_f32_e32 v31, v95, v109
	v_fmac_f32_e32 v14, v97, v107
	v_fmac_f32_e32 v15, v97, v109
	v_fmac_f32_e32 v28, v95, v117
	v_fmac_f32_e32 v29, v95, v119
	v_fmac_f32_e32 v12, v97, v117
	v_fmac_f32_e32 v13, v97, v119
	v_fmac_f32_e32 v26, v95, v121
	v_fmac_f32_e32 v27, v95, v123
	v_fmac_f32_e32 v10, v97, v121
	v_fmac_f32_e32 v11, v97, v123
	v_fmac_f32_e32 v24, v95, v143
	v_fmac_f32_e32 v25, v95, v145
	v_fmac_f32_e32 v8, v97, v143
	v_fmac_f32_e32 v9, v97, v145
	v_fmac_f32_e32 v22, v95, v147
	v_fmac_f32_e32 v23, v95, v149
	v_fmac_f32_e32 v6, v97, v147
	v_fmac_f32_e32 v7, v97, v149
	v_fmac_f32_e32 v20, v95, v151
	v_fmac_f32_e32 v21, v95, v153
	v_fmac_f32_e32 v2, v97, v151
	v_fmac_f32_e32 v3, v97, v153
	s_cmpk_lt_i32 s0, 0x100
	s_cbranch_scc1 .LBB0_210
	s_waitcnt lgkmcnt(0)
	s_movk_i32 s0, 0x100
	v_readlane_b32 s68, v165, 10
	v_lshlrev_b64 v[34:35], 2, v[34:35]
	v_readlane_b32 s80, v165, 22
	v_readlane_b32 s81, v165, 23
	v_readlane_b32 s74, v165, 16
	v_readlane_b32 s75, v165, 17
	v_lshl_add_u64 v[58:59], s[80:81], 0, v[34:35]
	global_load_dword v57, v[58:59], off
	v_readlane_b32 s78, v165, 20
	v_readlane_b32 s79, v165, 21
	v_lshl_add_u64 v[58:59], s[74:75], 0, v[34:35]
	global_load_dword v74, v[58:59], off
	v_lshl_add_u64 v[34:35], s[78:79], 0, v[34:35]
	global_load_dword v35, v[34:35], off
	v_readlane_b32 s69, v165, 11
	v_readlane_b32 s70, v165, 12
	v_readlane_b32 s71, v165, 13
	v_readlane_b32 s72, v165, 14
	v_readlane_b32 s73, v165, 15
	v_readlane_b32 s76, v165, 18
	v_readlane_b32 s77, v165, 19
	v_readlane_b32 s82, v165, 24
	v_readlane_b32 s83, v165, 25
	s_waitcnt vmcnt(2)
	v_mul_f32_e32 v34, 0xbfb8aa3b, v57
	v_exp_f32_e32 v34, v34
	s_nop 0
	v_cmp_ngt_f32_e32 vcc, s96, v34
	s_and_saveexec_b64 s[0:1], vcc
	s_xor_b64 s[22:23], exec, s[0:1]
	s_cbranch_execz .LBB0_213
	v_add_f32_e32 v34, 1.0, v34
	v_cmp_gt_f32_e32 vcc, s7, v34
	s_mov_b32 s0, 0x3f317217
	s_nop 0
	v_cndmask_b32_e64 v57, 0, 32, vcc
	v_ldexp_f32 v34, v34, v57
	v_log_f32_e32 v34, v34
	s_nop 0
	v_mul_f32_e32 v57, 0x3f317217, v34
	v_fma_f32 v57, v34, s0, -v57
	v_fmac_f32_e32 v57, 0x3377d1cf, v34
	s_mov_b32 s0, 0x7f800000
	v_fmac_f32_e32 v57, 0x3f317217, v34
	v_cmp_lt_f32_e64 s[0:1], |v34|, s0
	s_nop 1
	v_cndmask_b32_e64 v34, v34, v57, s[0:1]
	v_cndmask_b32_e32 v57, 0, v140, vcc
	v_sub_f32_e32 v75, v34, v57
